# P3 sample items: the 64 state loads per thread issued before the item's first barrier into free VGPRs, overlapping HBM latency with the gate math
# baseline (speedup 1.0000x reference)
; DEV float bf2f(unsigned b) { return __uint_as_float(b << 16); }
; DEV float silu_f(float x) { return x / (1.f + __expf(-x)); }
; DEV void gdn_sample_item(const Params& p, int item, unsigned char* lds) {
;     ...
;         for (int j = 0; j < 3; ++j) x[j] = p.in[6][((size_t)sb * 3 + j) * 3072 + col];
; #pragma unroll
;         for (int t = 0; t < 4; ++t) x[3 + t] = bf2f(proj[(size_t)(r0 + t) * NPJ + col]);
; #pragma unroll
;         for (int j = 0; j < 4; ++j) wj[j] = p.in[10][j * 3072 + col];
; #pragma unroll
;         for (int t = 0; t < 4; ++t) {
;             const float y = silu_f(wj[0] * x[t] + wj[1] * x[t + 1] + wj[2] * x[t + 2] + wj[3] * x[t + 3]);
;     ...
;     const float* sp0 = p.in[5] + ((size_t)(sb * 8 + h) * 128 + half * 64) * 128 + c;
; #pragma unroll
;     for (int d = 0; d < 64; ++d) S[d >> 1][d & 1] = __builtin_nontemporal_load(sp0 + (size_t)d * 128);
.LBB0_829:
	s_or_b64 exec, exec, s[6:7]
	v_mul_f32_e32 v6, v6, v27
	v_fmac_f32_e32 v6, v5, v20
	v_lshlrev_b32_e32 v21, 16, v21
	v_fmac_f32_e32 v6, v7, v28
	v_fmac_f32_e32 v6, v8, v21
	v_mul_f32_e32 v5, 0xbfb8aa3b, v6
	v_exp_f32_e32 v5, v5
	v_mul_f32_e32 v19, v19, v26
	v_fmac_f32_e32 v19, v18, v23
	s_waitcnt vmcnt(7)
	v_ashrrev_i32_e32 v182, 7, v97
	s_ashr_i32 s97, s52, 31
	s_mov_b32 s96, s52
	v_lshlrev_b32_e32 v182, 6, v182
	s_lshl_b64 s[96:97], s[96:97], 14
	v_ashrrev_i32_e32 v183, 31, v182
	v_lshlrev_b32_e32 v184, 2, v96
	v_lshlrev_b64 v[182:183], 7, v[182:183]
	v_mov_b32_e32 v185, 0
	v_lshl_add_u64 v[182:183], v[182:183], 0, s[96:97]
	s_mov_b64 s[96:97], 0x1000
	v_lshl_add_u64 v[182:183], v[182:183], 2, s[24:25]
	v_lshl_add_u64 v[182:183], v[182:183], 0, v[184:185]
	v_lshl_add_u64 v[182:183], v[182:183], 0, s[96:97]
	s_mov_b64 s[96:97], 0x2000
	global_load_dword v192, v[182:183], off offset:-4096 nt
	global_load_dword v193, v[182:183], off offset:-3584 nt
	global_load_dword v194, v[182:183], off offset:-3072 nt
	global_load_dword v195, v[182:183], off offset:-2560 nt
	global_load_dword v196, v[182:183], off offset:-2048 nt
	global_load_dword v197, v[182:183], off offset:-1536 nt
	global_load_dword v198, v[182:183], off offset:-1024 nt
	global_load_dword v199, v[182:183], off offset:-512 nt
	global_load_dword v200, v[182:183], off nt
	global_load_dword v201, v[182:183], off offset:512 nt
	global_load_dword v202, v[182:183], off offset:1024 nt
	global_load_dword v203, v[182:183], off offset:1536 nt
	global_load_dword v204, v[182:183], off offset:2048 nt
	global_load_dword v205, v[182:183], off offset:2560 nt
	global_load_dword v206, v[182:183], off offset:3072 nt
	global_load_dword v207, v[182:183], off offset:3584 nt
	v_lshl_add_u64 v[182:183], v[182:183], 0, s[96:97]
	global_load_dword v208, v[182:183], off offset:-4096 nt
	global_load_dword v209, v[182:183], off offset:-3584 nt
	global_load_dword v210, v[182:183], off offset:-3072 nt
	global_load_dword v211, v[182:183], off offset:-2560 nt
	global_load_dword v212, v[182:183], off offset:-2048 nt
	global_load_dword v213, v[182:183], off offset:-1536 nt
	global_load_dword v214, v[182:183], off offset:-1024 nt
	global_load_dword v215, v[182:183], off offset:-512 nt
	global_load_dword v216, v[182:183], off nt
	global_load_dword v217, v[182:183], off offset:512 nt
	global_load_dword v218, v[182:183], off offset:1024 nt
	global_load_dword v219, v[182:183], off offset:1536 nt
	global_load_dword v220, v[182:183], off offset:2048 nt
	global_load_dword v221, v[182:183], off offset:2560 nt
	global_load_dword v222, v[182:183], off offset:3072 nt
	global_load_dword v223, v[182:183], off offset:3584 nt
	v_lshl_add_u64 v[182:183], v[182:183], 0, s[96:97]
	global_load_dword v224, v[182:183], off offset:-4096 nt
	global_load_dword v225, v[182:183], off offset:-3584 nt
	global_load_dword v226, v[182:183], off offset:-3072 nt
	global_load_dword v227, v[182:183], off offset:-2560 nt
	global_load_dword v228, v[182:183], off offset:-2048 nt
	global_load_dword v229, v[182:183], off offset:-1536 nt
	global_load_dword v230, v[182:183], off offset:-1024 nt
	global_load_dword v231, v[182:183], off offset:-512 nt
	global_load_dword v232, v[182:183], off nt
	global_load_dword v233, v[182:183], off offset:512 nt
	global_load_dword v234, v[182:183], off offset:1024 nt
	global_load_dword v235, v[182:183], off offset:1536 nt
	global_load_dword v236, v[182:183], off offset:2048 nt
	global_load_dword v237, v[182:183], off offset:2560 nt
	global_load_dword v238, v[182:183], off offset:3072 nt
	global_load_dword v239, v[182:183], off offset:3584 nt
	v_lshl_add_u64 v[182:183], v[182:183], 0, s[96:97]
	global_load_dword v240, v[182:183], off offset:-4096 nt
	global_load_dword v241, v[182:183], off offset:-3584 nt
	global_load_dword v242, v[182:183], off offset:-3072 nt
	global_load_dword v243, v[182:183], off offset:-2560 nt
	global_load_dword v244, v[182:183], off offset:-2048 nt
	global_load_dword v245, v[182:183], off offset:-1536 nt
	global_load_dword v246, v[182:183], off offset:-1024 nt
	global_load_dword v247, v[182:183], off offset:-512 nt
	global_load_dword v248, v[182:183], off nt
	global_load_dword v249, v[182:183], off offset:512 nt
	global_load_dword v250, v[182:183], off offset:1024 nt
	global_load_dword v251, v[182:183], off offset:1536 nt
	global_load_dword v178, v[182:183], off offset:2048 nt
	global_load_dword v179, v[182:183], off offset:2560 nt
	global_load_dword v180, v[182:183], off offset:3072 nt
	global_load_dword v181, v[182:183], off offset:3584 nt
	v_lshlrev_b32_e32 v7, 16, v22
	v_add_f32_e32 v5, 1.0, v5


; DEV float silu_f(float x) { return x / (1.f + __expf(-x)); }
; DEV void gdn_sample_item(const Params& p, int item, unsigned char* lds) {
;     ...
;             const float y = silu_f(wj[0] * x[t] + wj[1] * x[t + 1] + wj[2] * x[t + 2] + wj[3] * x[t + 3]);
	v_fmac_f32_e32 v19, v11, v10
	v_fmac_f32_e32 v19, v12, v7
	v_mul_f32_e32 v7, 0xbfb8aa3b, v19
	v_exp_f32_e32 v7, v7


; DEV float silu_f(float x) { return x / (1.f + __expf(-x)); }
; DEV void gdn_sample_item(const Params& p, int item, unsigned char* lds) {
;     ...
;             const float y = silu_f(wj[0] * x[t] + wj[1] * x[t + 1] + wj[2] * x[t + 2] + wj[3] * x[t + 3]);
	s_nop 0
	v_add_f32_e32 v7, 1.0, v7


; DEV float silu_f(float x) { return x / (1.f + __expf(-x)); }
; DEV void gdn_sample_item(const Params& p, int item, unsigned char* lds) {
;     ...
;         for (int t = 0; t < 4; ++t) {
;             const float y = silu_f(wj[0] * x[t] + wj[1] * x[t + 1] + wj[2] * x[t + 2] + wj[3] * x[t + 3]);
;             if (m == 0) qv[t] = y; else if (m == 1) kv[t] = y; else vv[t] = y;
;         }
	v_rcp_f32_e32 v8, v5
	s_nop 0
	v_mul_f32_e32 v11, v6, v8


; DEV void gdn_sample_item(const Params& p, int item, unsigned char* lds) {
;     ...
; #pragma unroll
;     for (int t = 0; t < 4; ++t) {
;         const float a = wave_sum(qv[t] * qv[t]), bq = wave_sum(kv[t] * kv[t]);
;         if (lane == 0) { red[wid * 8 + t] = a; red[wid * 8 + 4 + t] = bq; }
;     }
	v_rcp_f32_e32 v5, v7
	s_nop 0
	v_mul_f32_e32 v12, v19, v5
	v_mul_f32_e32 v5, v11, v11
	v_mul_f32_e32 v6, v12, v12
	ds_bpermute_b32 v5, v98, v5
	ds_bpermute_b32 v6, v98, v6
	s_waitcnt lgkmcnt(1)
	v_fmac_f32_e32 v5, v11, v11
	s_waitcnt lgkmcnt(0)
	v_fmac_f32_e32 v6, v12, v12
	ds_bpermute_b32 v7, v99, v5
	ds_bpermute_b32 v8, v99, v6
	s_waitcnt lgkmcnt(1)
	v_add_f32_e32 v5, v5, v7
	s_waitcnt lgkmcnt(0)
	v_add_f32_e32 v6, v6, v8
	ds_bpermute_b32 v7, v100, v5
	ds_bpermute_b32 v8, v100, v6
	s_waitcnt lgkmcnt(1)
	v_add_f32_e32 v5, v5, v7
	s_waitcnt lgkmcnt(0)
	v_add_f32_e32 v6, v6, v8
	ds_bpermute_b32 v7, v101, v5
	ds_bpermute_b32 v8, v101, v6
	s_waitcnt lgkmcnt(1)
	v_add_f32_e32 v5, v5, v7
	s_waitcnt lgkmcnt(0)
	v_add_f32_e32 v8, v6, v8
	ds_bpermute_b32 v7, v102, v5
	ds_bpermute_b32 v10, v102, v8
	s_waitcnt lgkmcnt(1)
	v_add_f32_e32 v5, v5, v7
	s_waitcnt lgkmcnt(0)
	v_add_f32_e32 v7, v8, v10
	ds_bpermute_b32 v6, v103, v5
	ds_bpermute_b32 v8, v103, v7
	s_and_saveexec_b64 s[6:7], s[4:5]
	s_cbranch_execz .LBB0_831
	s_waitcnt lgkmcnt(1)
	v_add_f32_e32 v5, v5, v6
	s_waitcnt lgkmcnt(0)
	v_add_f32_e32 v6, v7, v8
	v_add_u32_e32 v7, 0x1000, v24
	ds_write2_b32 v7, v5, v6 offset0:3 offset1:7

; DEV void gdn_sample_item(const Params& p, int item, unsigned char* lds) {
;     ...
;         float a = 0.f, bb = 0.f;
; #pragma unroll
;         for (int kq = 0; kq < 4; ++kq) { a += ab[(size_t)kq * TT * 16 + (size_t)(r0 + t) * 16 + h]; bb += ab[(size_t)kq * TT * 16 + (size_t)(r0 + t) * 16 + 8 + h]; }
;         const float xx = a + p.in[12][h];
;         const float sp = xx > 20.f ? xx : log1pf(__expf(xx));
;         gt[t] = __expf(-__expf(p.in[11][h]) * sp);
;         bt[t] = 1.f / (1.f + __expf(-bb));
;     }
;     f32x2_t S[32];
;     const float* sp0 = p.in[5] + ((size_t)(sb * 8 + h) * 128 + half * 64) * 128 + c;
.LBB0_848:
	v_add_f32_e32 v2, 0, v2
	v_add_f32_e32 v2, v2, v6
	v_add_f32_e32 v2, v2, v7
	v_add_f32_e32 v2, v2, v8
	v_mul_f32_e32 v2, 0xbfb8aa3b, v2
	v_exp_f32_e32 v2, v2
	v_ashrrev_i32_e32 v154, 7, v97
	v_lshlrev_b32_e32 v6, 6, v154
	v_mul_f32_e32 v5, v10, v13
	v_add_f32_e32 v132, 1.0, v2


; DEV void gdn_sample_item(const Params& p, int item, unsigned char* lds) {
;     ...
;         const float xx = a + p.in[12][h];
;         const float sp = xx > 20.f ? xx : log1pf(__expf(xx));
;         gt[t] = __expf(-__expf(p.in[11][h]) * sp);
;         bt[t] = 1.f / (1.f + __expf(-bb));
;     }
;     f32x2_t S[32];
;     const float* sp0 = p.in[5] + ((size_t)(sb * 8 + h) * 128 + half * 64) * 128 + c;
	s_ashr_i32 s53, s52, 31
	v_ashrrev_i32_e32 v7, 31, v6
	v_mul_f32_e32 v2, 0x3fb8aa3b, v5
	s_lshl_b64 s[8:9], s[52:53], 14
	v_lshlrev_b64 v[6:7], 7, v[6:7]
	v_exp_f32_e32 v8, v2

; DEV void gdn_sample_item(const Params& p, int item, unsigned char* lds) {
;     ...
;     const float* sp0 = p.in[5] + ((size_t)(sb * 8 + h) * 128 + half * 64) * 128 + c;
	v_lshl_add_u64 v[6:7], v[6:7], 0, s[8:9]

; DEV void gdn_sample_item(const Params& p, int item, unsigned char* lds) {
;     ...
;     const float* sp0 = p.in[5] + ((size_t)(sb * 8 + h) * 128 + half * 64) * 128 + c;
; #pragma unroll
;     for (int d = 0; d < 64; ++d) S[d >> 1][d & 1] = __builtin_nontemporal_load(sp0 + (size_t)d * 128);
	v_lshl_add_u64 v[10:11], v[6:7], 2, s[24:25]
	v_lshlrev_b32_e32 v2, 2, v96
	v_lshl_add_u64 v[66:67], v[10:11], 0, v[2:3]
	v_add_co_u32_e32 v28, vcc, s85, v66


; DEV float silu_f(float x) { return x / (1.f + __expf(-x)); }
; DEV void gdn_sample_item(const Params& p, int item, unsigned char* lds) {
;     ...
;         for (int t = 0; t < 4; ++t) {
;             const float y = silu_f(wj[0] * x[t] + wj[1] * x[t + 1] + wj[2] * x[t + 2] + wj[3] * x[t + 3]);
;             if (m == 0) qv[t] = y; else if (m == 1) kv[t] = y; else vv[t] = y;
;     ...
;     const float* sp0 = p.in[5] + ((size_t)(sb * 8 + h) * 128 + half * 64) * 128 + c;
; #pragma unroll
;     for (int d = 0; d < 64; ++d) S[d >> 1][d & 1] = __builtin_nontemporal_load(sp0 + (size_t)d * 128);
	s_nop 1
	v_addc_co_u32_e32 v29, vcc, 0, v67, vcc
	v_add_co_u32_e32 v36, vcc, s65, v66
	v_mul_f32_e32 v155, v109, v76
	s_nop 0
	v_addc_co_u32_e32 v37, vcc, 0, v67, vcc


; DEV float silu_f(float x) { return x / (1.f + __expf(-x)); }
; DEV void gdn_sample_item(const Params& p, int item, unsigned char* lds) {
;     ...
;         for (int t = 0; t < 4; ++t) {
;             const float y = silu_f(wj[0] * x[t] + wj[1] * x[t + 1] + wj[2] * x[t + 2] + wj[3] * x[t + 3]);
;             if (m == 0) qv[t] = y; else if (m == 1) kv[t] = y; else vv[t] = y;
;     ...
;     const float* sp0 = p.in[5] + ((size_t)(sb * 8 + h) * 128 + half * 64) * 128 + c;
; #pragma unroll
;     for (int d = 0; d < 64; ++d) S[d >> 1][d & 1] = __builtin_nontemporal_load(sp0 + (size_t)d * 128);
	v_add_co_u32_e32 v52, vcc, s66, v66
	v_fmac_f32_e32 v155, v9, v77
	s_nop 0
	v_addc_co_u32_e32 v53, vcc, 0, v67, vcc
	v_add_co_u32_e32 v38, vcc, s68, v66
	v_fmac_f32_e32 v155, v107, v75
	s_nop 0
	v_addc_co_u32_e32 v39, vcc, 0, v67, vcc


; DEV void gdn_sample_item(const Params& p, int item, unsigned char* lds) {
;     ...
;     const float* sp0 = p.in[5] + ((size_t)(sb * 8 + h) * 128 + half * 64) * 128 + c;
; #pragma unroll
;     for (int d = 0; d < 64; ++d) S[d >> 1][d & 1] = __builtin_nontemporal_load(sp0 + (size_t)d * 128);
	s_nop 0


; DEV void gdn_sample_item(const Params& p, int item, unsigned char* lds) {
;     ...
;     const float* sp0 = p.in[5] + ((size_t)(sb * 8 + h) * 128 + half * 64) * 128 + c;
; #pragma unroll
;     for (int d = 0; d < 64; ++d) S[d >> 1][d & 1] = __builtin_nontemporal_load(sp0 + (size_t)d * 128);
	v_add_co_u32_e32 v58, vcc, s74, v66
	s_nop 1
	v_addc_co_u32_e32 v59, vcc, 0, v67, vcc
	v_add_co_u32_e32 v68, vcc, s67, v66
	s_nop 1
	v_addc_co_u32_e32 v69, vcc, 0, v67, vcc


; DEV void gdn_sample_item(const Params& p, int item, unsigned char* lds) {
;     ...
;     const float* sp0 = p.in[5] + ((size_t)(sb * 8 + h) * 128 + half * 64) * 128 + c;
; #pragma unroll
;     for (int d = 0; d < 64; ++d) S[d >> 1][d & 1] = __builtin_nontemporal_load(sp0 + (size_t)d * 128);
	s_nop 0


; DEV void gdn_sample_item(const Params& p, int item, unsigned char* lds) {
;     ...
;     const float* sp0 = p.in[5] + ((size_t)(sb * 8 + h) * 128 + half * 64) * 128 + c;
; #pragma unroll
;     for (int d = 0; d < 64; ++d) S[d >> 1][d & 1] = __builtin_nontemporal_load(sp0 + (size_t)d * 128);
	s_nop 0


; DEV void gdn_sample_item(const Params& p, int item, unsigned char* lds) {
;     ...
;     const float* sp0 = p.in[5] + ((size_t)(sb * 8 + h) * 128 + half * 64) * 128 + c;
; #pragma unroll
;     for (int d = 0; d < 64; ++d) S[d >> 1][d & 1] = __builtin_nontemporal_load(sp0 + (size_t)d * 128);
	s_nop 0


; DEV void gdn_sample_item(const Params& p, int item, unsigned char* lds) {
;     ...
;     const float* sp0 = p.in[5] + ((size_t)(sb * 8 + h) * 128 + half * 64) * 128 + c;
; #pragma unroll
;     for (int d = 0; d < 64; ++d) S[d >> 1][d & 1] = __builtin_nontemporal_load(sp0 + (size_t)d * 128);
	v_add_co_u32_e32 v130, vcc, s69, v66
	s_nop 1
	v_addc_co_u32_e32 v131, vcc, 0, v67, vcc


; DEV float silu_f(float x) { return x / (1.f + __expf(-x)); }
; DEV void gdn_sample_item(const Params& p, int item, unsigned char* lds) {
;     ...
;         for (int t = 0; t < 4; ++t) {
;             const float y = silu_f(wj[0] * x[t] + wj[1] * x[t + 1] + wj[2] * x[t + 2] + wj[3] * x[t + 3]);
;             if (m == 0) qv[t] = y; else if (m == 1) kv[t] = y; else vv[t] = y;
	v_lshlrev_b32_e32 v130, 16, v111
	v_fmac_f32_e32 v155, v74, v130
	v_mul_f32_e32 v9, 0xbfb8aa3b, v155
	v_exp_f32_e32 v9, v9


; DEV float silu_f(float x) { return x / (1.f + __expf(-x)); }
; DEV void gdn_sample_item(const Params& p, int item, unsigned char* lds) {
;     ...
;             const float y = silu_f(wj[0] * x[t] + wj[1] * x[t + 1] + wj[2] * x[t + 2] + wj[3] * x[t + 3]);
	s_nop 0
	v_add_f32_e32 v9, 1.0, v9


; DEV void gdn_sample_item(const Params& p, int item, unsigned char* lds) {
;     ...
;         bt[t] = 1.f / (1.f + __expf(-bb));
;     ...
;     __syncthreads();
;     ...
;         const float* kk = ksh + t * 128 + half * 64; const float* qq = qsh + t * 128 + half * 64;
;         f32x2_t ks2 = {0.f, 0.f};
; #pragma unroll
;         for (int d4 = 0; d4 < 16; ++d4) { const f32x4 k4 = *(const f32x4*)(kk + d4 * 4); ks2 += (f32x2_t){k4[0], k4[1]} * S[d4 * 2]; ks2 += (f32x2_t){k4[2], k4[3]} * S[d4 * 2 + 1]; }
	v_lshl_add_u32 v111, v154, 8, s70
	v_rcp_f32_e32 v5, v132
	s_nop 0
	v_mul_f32_e32 v5, 1.0, v5
	s_waitcnt lgkmcnt(0)
	s_barrier
	ds_read_b128 v[132:135], v111
	ds_read_b128 v[142:145], v111 offset:16
	ds_read_b128 v[146:149], v111 offset:32
	ds_read_b128 v[150:153], v111 offset:48

; DEV void gdn_sample_item(const Params& p, int item, unsigned char* lds) {
;     ...
;         const float* kk = ksh + t * 128 + half * 64; const float* qq = qsh + t * 128 + half * 64;
;         f32x2_t ks2 = {0.f, 0.f};
; #pragma unroll
;         for (int d4 = 0; d4 < 16; ++d4) { const f32x4 k4 = *(const f32x4*)(kk + d4 * 4); ks2 += (f32x2_t){k4[0], k4[1]} * S[d4 * 2]; ks2 += (f32x2_t){k4[2], k4[3]} * S[d4 * 2 + 1]; }
;         part[(t * 2 + half) * 128 + c] = ks2[0] + ks2[1];
	v_cmp_eq_u32_e64 s[8:9], 1, v154
	s_waitcnt vmcnt(62) lgkmcnt(3)
	v_pk_fma_f32 v[132:133], v[192:193], v[132:133], 0 op_sel_hi:[1,1,0]
	s_waitcnt vmcnt(60)
	v_pk_fma_f32 v[132:133], v[194:195], v[134:135], v[132:133]
	s_waitcnt vmcnt(58) lgkmcnt(2)
	v_pk_fma_f32 v[132:133], v[196:197], v[142:143], v[132:133]
	s_waitcnt vmcnt(56)
	v_pk_fma_f32 v[132:133], v[198:199], v[144:145], v[132:133]
	ds_read_b128 v[142:145], v111 offset:80
	s_waitcnt vmcnt(52) lgkmcnt(2)
	v_pk_fma_f32 v[136:137], v[200:201], v[146:147], v[132:133]
	ds_read_b128 v[132:135], v111 offset:64
	s_waitcnt vmcnt(50)
	v_pk_fma_f32 v[136:137], v[202:203], v[148:149], v[136:137]
	ds_read_b128 v[146:149], v111 offset:96
	s_waitcnt vmcnt(48) lgkmcnt(3)
	v_pk_fma_f32 v[136:137], v[204:205], v[150:151], v[136:137]
	s_waitcnt vmcnt(46)
	v_pk_fma_f32 v[136:137], v[206:207], v[152:153], v[136:137]
	s_waitcnt lgkmcnt(1)
	v_pk_fma_f32 v[132:133], v[208:209], v[132:133], v[136:137]
	s_waitcnt vmcnt(43)
	v_pk_fma_f32 v[132:133], v[210:211], v[134:135], v[132:133]
	s_waitcnt vmcnt(41)
	v_pk_fma_f32 v[136:137], v[212:213], v[142:143], v[132:133]
	ds_read_b128 v[132:135], v111 offset:112
	s_waitcnt vmcnt(39)
	v_pk_fma_f32 v[136:137], v[214:215], v[144:145], v[136:137]
	ds_read_b128 v[142:145], v111 offset:128
	s_waitcnt vmcnt(38) lgkmcnt(2)
	v_pk_fma_f32 v[136:137], v[216:217], v[146:147], v[136:137]
	s_waitcnt vmcnt(27)
	v_pk_fma_f32 v[136:137], v[218:219], v[148:149], v[136:137]
	ds_read_b128 v[146:149], v111 offset:144
	s_waitcnt vmcnt(25) lgkmcnt(2)
	v_pk_fma_f32 v[132:133], v[220:221], v[132:133], v[136:137]
	s_waitcnt vmcnt(23)
	v_pk_fma_f32 v[132:133], v[222:223], v[134:135], v[132:133]
	s_waitcnt lgkmcnt(1)
	v_pk_fma_f32 v[136:137], v[224:225], v[142:143], v[132:133]
	ds_read_b128 v[132:135], v111 offset:160
	v_pk_fma_f32 v[136:137], v[226:227], v[144:145], v[136:137]
	ds_read_b128 v[142:145], v111 offset:176
	s_waitcnt lgkmcnt(2)
	v_pk_fma_f32 v[136:137], v[228:229], v[146:147], v[136:137]
	s_nop 0
	v_pk_fma_f32 v[136:137], v[230:231], v[148:149], v[136:137]
	ds_read_b128 v[146:149], v111 offset:192
	s_waitcnt vmcnt(22) lgkmcnt(2)
	v_pk_fma_f32 v[132:133], v[232:233], v[132:133], v[136:137]
	s_waitcnt vmcnt(20)
	v_pk_fma_f32 v[132:133], v[234:235], v[134:135], v[132:133]
	s_waitcnt vmcnt(18) lgkmcnt(1)
	v_pk_fma_f32 v[132:133], v[236:237], v[142:143], v[132:133]
	s_waitcnt vmcnt(16)
	v_pk_fma_f32 v[136:137], v[238:239], v[144:145], v[132:133]
	ds_read_b128 v[132:135], v111 offset:208
	ds_read_b128 v[142:145], v111 offset:224
	s_waitcnt vmcnt(14) lgkmcnt(2)
	v_pk_fma_f32 v[136:137], v[240:241], v[146:147], v[136:137]
	s_waitcnt vmcnt(12)
	v_pk_fma_f32 v[136:137], v[242:243], v[148:149], v[136:137]
	ds_read_b128 v[146:149], v111 offset:240
	s_waitcnt vmcnt(10) lgkmcnt(2)
	v_pk_fma_f32 v[132:133], v[244:245], v[132:133], v[136:137]
	s_waitcnt vmcnt(8)
	v_pk_fma_f32 v[132:133], v[246:247], v[134:135], v[132:133]

; DEV void gdn_sample_item(const Params& p, int item, unsigned char* lds) {
;     ...
;         for (int d4 = 0; d4 < 16; ++d4) { const f32x4 k4 = *(const f32x4*)(kk + d4 * 4); ks2 += (f32x2_t){k4[0], k4[1]} * S[d4 * 2]; ks2 += (f32x2_t){k4[2], k4[3]} * S[d4 * 2 + 1]; }
;         part[(t * 2 + half) * 128 + c] = ks2[0] + ks2[1];
;         __syncthreads();
;         const float kS = part[(t * 2) * 128 + c] + part[(t * 2 + 1) * 128 + c];
;         const float eg = gt[t], dl = bt[t] * (vv[t] - eg * kS);
;         const f32x2_t eg2 = {eg, eg}, dl2 = {dl, dl};
;         f32x2_t o2 = {0.f, 0.f};
; #pragma unroll
;         for (int d4 = 0; d4 < 16; ++d4) {
;             const f32x4 k4 = *(const f32x4*)(kk + d4 * 4), q4 = *(const f32x4*)(qq + d4 * 4);
;             const f32x2_t s0 = S[d4 * 2] * eg2 + (f32x2_t){k4[0], k4[1]} * dl2, s1 = S[d4 * 2 + 1] * eg2 + (f32x2_t){k4[2], k4[3]} * dl2;
;             S[d4 * 2] = s0; S[d4 * 2 + 1] = s1;
;             o2 += (f32x2_t){q4[0], q4[1]} * s0; o2 += (f32x2_t){q4[2], q4[3]} * s1;
	s_waitcnt vmcnt(6) lgkmcnt(1)
	v_pk_fma_f32 v[132:133], v[248:249], v[142:143], v[132:133]
	v_rcp_f32_e32 v134, v9
	s_nop 0
	v_mul_f32_e32 v9, v155, v134
	s_waitcnt vmcnt(4)
	v_pk_fma_f32 v[132:133], v[250:251], v[144:145], v[132:133]
	s_waitcnt vmcnt(2) lgkmcnt(0)
	v_pk_fma_f32 v[132:133], v[178:179], v[146:147], v[132:133]
	s_waitcnt vmcnt(0)
	v_pk_fma_f32 v[132:133], v[180:181], v[148:149], v[132:133]
	s_nop 0
	v_add_f32_e32 v131, v132, v133
	ds_write_b32 v105, v131 offset:4352
	v_add_u32_e32 v131, s70, v2
	s_waitcnt lgkmcnt(0)
	s_barrier
	ds_read2st64_b32 v[132:133], v131 offset0:17 offset1:19
	s_waitcnt lgkmcnt(0)
	v_add_f32_e32 v132, v132, v133
	v_fma_f32 v9, -v8, v132, v9
	v_mul_f32_e32 v136, v5, v9
	ds_read_b128 v[132:135], v111
	ds_read_b128 v[142:145], v111 offset:16
	ds_read_b128 v[146:149], v111 offset:32
	ds_read_b128 v[150:153], v111 offset:48
	ds_read_b128 v[154:157], v111 offset:2048
	s_waitcnt lgkmcnt(4)
	v_pk_mul_f32 v[132:133], v[132:133], v[136:137] op_sel_hi:[1,0]
	s_waitcnt lgkmcnt(3)
	v_pk_mul_f32 v[142:143], v[142:143], v[136:137] op_sel_hi:[1,0]
	v_pk_fma_f32 v[10:11], v[8:9], v[192:193], v[132:133] op_sel_hi:[0,1,1]
	v_pk_mul_f32 v[132:133], v[134:135], v[136:137] op_sel_hi:[1,0]
	s_waitcnt lgkmcnt(0)
	v_pk_fma_f32 v[154:155], v[154:155], v[10:11], 0 op_sel_hi:[1,1,0]
	v_pk_fma_f32 v[12:13], v[8:9], v[194:195], v[132:133] op_sel_hi:[0,1,1]
	ds_read_b128 v[132:135], v111 offset:2064
	v_pk_fma_f32 v[154:155], v[156:157], v[12:13], v[154:155]
	v_pk_fma_f32 v[14:15], v[8:9], v[196:197], v[142:143] op_sel_hi:[0,1,1]
	v_pk_mul_f32 v[142:143], v[144:145], v[136:137] op_sel_hi:[1,0]
	s_waitcnt lgkmcnt(0)
	v_pk_fma_f32 v[132:133], v[132:133], v[14:15], v[154:155]
	v_pk_fma_f32 v[16:17], v[8:9], v[198:199], v[142:143] op_sel_hi:[0,1,1]
	v_pk_fma_f32 v[154:155], v[134:135], v[16:17], v[132:133]
	ds_read_b128 v[132:135], v111 offset:2080
	v_pk_mul_f32 v[142:143], v[136:137], v[146:147] op_sel_hi:[0,1]
	v_pk_fma_f32 v[18:19], v[8:9], v[200:201], v[142:143] op_sel_hi:[0,1,1]
	v_pk_mul_f32 v[142:143], v[136:137], v[148:149] op_sel_hi:[0,1]
	v_pk_fma_f32 v[20:21], v[8:9], v[202:203], v[142:143] op_sel_hi:[0,1,1]
	ds_read_b128 v[142:145], v111 offset:2096
	s_waitcnt lgkmcnt(1)
	v_pk_fma_f32 v[132:133], v[132:133], v[18:19], v[154:155]
	s_nop 0
	v_pk_fma_f32 v[146:147], v[134:135], v[20:21], v[132:133]
	v_pk_mul_f32 v[132:133], v[136:137], v[150:151] op_sel_hi:[0,1]
	v_pk_fma_f32 v[22:23], v[8:9], v[204:205], v[132:133] op_sel_hi:[0,1,1]
	v_pk_mul_f32 v[132:133], v[136:137], v[152:153] op_sel_hi:[0,1]
	v_pk_fma_f32 v[24:25], v[8:9], v[206:207], v[132:133] op_sel_hi:[0,1,1]
	ds_read_b128 v[132:135], v111 offset:64
	s_waitcnt lgkmcnt(1)
	v_pk_fma_f32 v[142:143], v[142:143], v[22:23], v[146:147]
	s_waitcnt lgkmcnt(0)
	v_pk_mul_f32 v[132:133], v[136:137], v[132:133] op_sel_hi:[0,1]
	v_pk_fma_f32 v[150:151], v[144:145], v[24:25], v[142:143]
	ds_read_b128 v[142:145], v111 offset:2112
	ds_read_b128 v[146:149], v111 offset:80
	v_pk_fma_f32 v[26:27], v[8:9], v[208:209], v[132:133] op_sel_hi:[0,1,1]
	v_pk_mul_f32 v[132:133], v[136:137], v[134:135] op_sel_hi:[0,1]
	v_pk_fma_f32 v[28:29], v[8:9], v[210:211], v[132:133] op_sel_hi:[0,1,1]
	ds_read_b128 v[132:135], v111 offset:2128
	s_waitcnt lgkmcnt(2)
	v_pk_fma_f32 v[142:143], v[142:143], v[26:27], v[150:151]
	s_nop 0
	v_pk_fma_f32 v[150:151], v[144:145], v[28:29], v[142:143]
	s_waitcnt lgkmcnt(1)
	v_pk_mul_f32 v[142:143], v[136:137], v[146:147] op_sel_hi:[0,1]
	v_pk_fma_f32 v[30:31], v[8:9], v[212:213], v[142:143] op_sel_hi:[0,1,1]
	v_pk_mul_f32 v[142:143], v[136:137], v[148:149] op_sel_hi:[0,1]
	v_pk_fma_f32 v[32:33], v[8:9], v[214:215], v[142:143] op_sel_hi:[0,1,1]
	ds_read_b128 v[142:145], v111 offset:96
	s_waitcnt lgkmcnt(1)
	v_pk_fma_f32 v[132:133], v[132:133], v[30:31], v[150:151]
	s_waitcnt lgkmcnt(0)
	v_pk_mul_f32 v[142:143], v[136:137], v[142:143] op_sel_hi:[0,1]
	v_pk_fma_f32 v[150:151], v[134:135], v[32:33], v[132:133]
	ds_read_b128 v[132:135], v111 offset:2144
	ds_read_b128 v[146:149], v111 offset:112
	v_pk_fma_f32 v[34:35], v[8:9], v[216:217], v[142:143] op_sel_hi:[0,1,1]
	v_pk_mul_f32 v[142:143], v[136:137], v[144:145] op_sel_hi:[0,1]
	v_pk_fma_f32 v[36:37], v[8:9], v[218:219], v[142:143] op_sel_hi:[0,1,1]
	ds_read_b128 v[142:145], v111 offset:2160
	s_waitcnt lgkmcnt(2)
	v_pk_fma_f32 v[132:133], v[132:133], v[34:35], v[150:151]
	s_nop 0
	v_pk_fma_f32 v[150:151], v[134:135], v[36:37], v[132:133]
	s_waitcnt lgkmcnt(1)
	v_pk_mul_f32 v[132:133], v[136:137], v[146:147] op_sel_hi:[0,1]
	v_pk_fma_f32 v[38:39], v[8:9], v[220:221], v[132:133] op_sel_hi:[0,1,1]
	v_pk_mul_f32 v[132:133], v[136:137], v[148:149] op_sel_hi:[0,1]
	v_pk_fma_f32 v[40:41], v[8:9], v[222:223], v[132:133] op_sel_hi:[0,1,1]
	ds_read_b128 v[132:135], v111 offset:128
	s_waitcnt lgkmcnt(1)
; DEV float silu_f(float x) { return x / (1.f + __expf(-x)); }
; DEV void gdn_sample_item(const Params& p, int item, unsigned char* lds) {
;     ...
;         for (int t = 0; t < 4; ++t) {
;             const float y = silu_f(wj[0] * x[t] + wj[1] * x[t + 1] + wj[2] * x[t + 2] + wj[3] * x[t + 3]);
;             if (m == 0) qv[t] = y; else if (m == 1) kv[t] = y; else vv[t] = y;
;     ...
;         float a = 0.f, bb = 0.f;
; #pragma unroll
;         for (int kq = 0; kq < 4; ++kq) { a += ab[(size_t)kq * TT * 16 + (size_t)(r0 + t) * 16 + h]; bb += ab[(size_t)kq * TT * 16 + (size_t)(r0 + t) * 16 + 8 + h]; }
;         const float xx = a + p.in[12][h];
;         const float sp = xx > 20.f ? xx : log1pf(__expf(xx));
;         gt[t] = __expf(-__expf(p.in[11][h]) * sp);
;         bt[t] = 1.f / (1.f + __expf(-bb));
;     ...
;         for (int d4 = 0; d4 < 16; ++d4) {
;             const f32x4 k4 = *(const f32x4*)(kk + d4 * 4), q4 = *(const f32x4*)(qq + d4 * 4);
;             const f32x2_t s0 = S[d4 * 2] * eg2 + (f32x2_t){k4[0], k4[1]} * dl2, s1 = S[d4 * 2 + 1] * eg2 + (f32x2_t){k4[2], k4[3]} * dl2;
;             S[d4 * 2] = s0; S[d4 * 2 + 1] = s1;
;             o2 += (f32x2_t){q4[0], q4[1]} * s0; o2 += (f32x2_t){q4[2], q4[3]} * s1;
;         }
;         const float o = o2[0] + o2[1];
;         ot[t] = o;
;         if (half == 1) opart[t * 128 + c] = o;
;     }
	v_pk_fma_f32 v[142:143], v[142:143], v[38:39], v[150:151]
	s_waitcnt lgkmcnt(0)
	v_pk_mul_f32 v[132:133], v[136:137], v[132:133] op_sel_hi:[0,1]
	v_pk_fma_f32 v[150:151], v[144:145], v[40:41], v[142:143]
	ds_read_b128 v[142:145], v111 offset:2176
	ds_read_b128 v[146:149], v111 offset:144
	v_pk_fma_f32 v[42:43], v[8:9], v[224:225], v[132:133] op_sel_hi:[0,1,1]
	v_pk_mul_f32 v[132:133], v[136:137], v[134:135] op_sel_hi:[0,1]
	v_pk_fma_f32 v[44:45], v[8:9], v[226:227], v[132:133] op_sel_hi:[0,1,1]
	ds_read_b128 v[132:135], v111 offset:2192
	s_waitcnt lgkmcnt(2)
	v_pk_fma_f32 v[142:143], v[142:143], v[42:43], v[150:151]
	s_nop 0
	v_pk_fma_f32 v[150:151], v[144:145], v[44:45], v[142:143]
	s_waitcnt lgkmcnt(1)
	v_pk_mul_f32 v[142:143], v[136:137], v[146:147] op_sel_hi:[0,1]
	v_pk_fma_f32 v[46:47], v[8:9], v[228:229], v[142:143] op_sel_hi:[0,1,1]
	v_pk_mul_f32 v[142:143], v[136:137], v[148:149] op_sel_hi:[0,1]
	v_pk_fma_f32 v[48:49], v[8:9], v[230:231], v[142:143] op_sel_hi:[0,1,1]
	ds_read_b128 v[142:145], v111 offset:160
	s_waitcnt lgkmcnt(1)
	v_pk_fma_f32 v[132:133], v[132:133], v[46:47], v[150:151]
	s_waitcnt lgkmcnt(0)
	v_pk_mul_f32 v[142:143], v[136:137], v[142:143] op_sel_hi:[0,1]
	v_pk_fma_f32 v[150:151], v[134:135], v[48:49], v[132:133]
	ds_read_b128 v[132:135], v111 offset:2208
	ds_read_b128 v[146:149], v111 offset:176
	v_pk_fma_f32 v[50:51], v[8:9], v[232:233], v[142:143] op_sel_hi:[0,1,1]
	v_pk_mul_f32 v[142:143], v[136:137], v[144:145] op_sel_hi:[0,1]
	v_pk_fma_f32 v[52:53], v[8:9], v[234:235], v[142:143] op_sel_hi:[0,1,1]
	ds_read_b128 v[142:145], v111 offset:2224
	s_waitcnt lgkmcnt(2)
	v_pk_fma_f32 v[132:133], v[132:133], v[50:51], v[150:151]
	s_nop 0
	v_pk_fma_f32 v[150:151], v[134:135], v[52:53], v[132:133]
	s_waitcnt lgkmcnt(1)
	v_pk_mul_f32 v[132:133], v[136:137], v[146:147] op_sel_hi:[0,1]
	v_pk_fma_f32 v[54:55], v[8:9], v[236:237], v[132:133] op_sel_hi:[0,1,1]
	v_pk_mul_f32 v[132:133], v[136:137], v[148:149] op_sel_hi:[0,1]
	v_pk_fma_f32 v[56:57], v[8:9], v[238:239], v[132:133] op_sel_hi:[0,1,1]
	ds_read_b128 v[132:135], v111 offset:192
	s_waitcnt lgkmcnt(1)
	v_pk_fma_f32 v[142:143], v[142:143], v[54:55], v[150:151]
	s_waitcnt lgkmcnt(0)
	v_pk_mul_f32 v[132:133], v[136:137], v[132:133] op_sel_hi:[0,1]
	v_pk_fma_f32 v[150:151], v[144:145], v[56:57], v[142:143]
	ds_read_b128 v[142:145], v111 offset:2240
	ds_read_b128 v[146:149], v111 offset:208
	v_pk_fma_f32 v[58:59], v[8:9], v[240:241], v[132:133] op_sel_hi:[0,1,1]
	v_pk_mul_f32 v[132:133], v[136:137], v[134:135] op_sel_hi:[0,1]
	v_pk_fma_f32 v[60:61], v[8:9], v[242:243], v[132:133] op_sel_hi:[0,1,1]
	s_waitcnt lgkmcnt(1)
	v_pk_fma_f32 v[142:143], v[142:143], v[58:59], v[150:151]
	ds_read_b128 v[132:135], v111 offset:2256
	v_pk_fma_f32 v[150:151], v[144:145], v[60:61], v[142:143]
	s_waitcnt lgkmcnt(1)
	v_pk_mul_f32 v[142:143], v[136:137], v[146:147] op_sel_hi:[0,1]
	v_pk_fma_f32 v[62:63], v[8:9], v[244:245], v[142:143] op_sel_hi:[0,1,1]
	v_pk_mul_f32 v[142:143], v[136:137], v[148:149] op_sel_hi:[0,1]
	v_pk_fma_f32 v[64:65], v[8:9], v[246:247], v[142:143] op_sel_hi:[0,1,1]
	ds_read_b128 v[142:145], v111 offset:224
	s_waitcnt lgkmcnt(1)
	v_pk_fma_f32 v[132:133], v[132:133], v[62:63], v[150:151]
	s_waitcnt lgkmcnt(0)
	v_pk_mul_f32 v[142:143], v[136:137], v[142:143] op_sel_hi:[0,1]
	v_pk_fma_f32 v[150:151], v[134:135], v[64:65], v[132:133]
	ds_read_b128 v[132:135], v111 offset:2272
	ds_read_b128 v[146:149], v111 offset:240
	v_pk_fma_f32 v[66:67], v[8:9], v[248:249], v[142:143] op_sel_hi:[0,1,1]
	v_pk_mul_f32 v[142:143], v[136:137], v[144:145] op_sel_hi:[0,1]
	v_pk_fma_f32 v[68:69], v[8:9], v[250:251], v[142:143] op_sel_hi:[0,1,1]
	ds_read_b128 v[142:145], v111 offset:2288
	s_waitcnt lgkmcnt(2)
	v_pk_fma_f32 v[132:133], v[132:133], v[66:67], v[150:151]
	s_nop 0
	v_pk_fma_f32 v[132:133], v[134:135], v[68:69], v[132:133]
	s_waitcnt lgkmcnt(1)
	v_pk_mul_f32 v[134:135], v[136:137], v[146:147] op_sel_hi:[0,1]
	v_pk_fma_f32 v[70:71], v[8:9], v[178:179], v[134:135] op_sel_hi:[0,1,1]
	v_pk_mul_f32 v[134:135], v[136:137], v[148:149] op_sel_hi:[0,1]
	v_pk_fma_f32 v[8:9], v[8:9], v[180:181], v[134:135] op_sel_hi:[0,1,1]
	s_waitcnt lgkmcnt(0)
	v_pk_fma_f32 v[72:73], v[142:143], v[70:71], v[132:133]
	s_nop 0
	v_pk_fma_f32 v[72:73], v[144:145], v[8:9], v[72:73]
	s_nop 0
	v_add_f32_e32 v5, v72, v73
	s_and_saveexec_b64 s[52:53], s[8:9]
	ds_write_b32 v131, v5 offset:8448
	s_or_b64 exec, exec, s[52:53]
	v_add_f32_e32 v72, 0, v120
	v_add_f32_e32 v72, v72, v121
	v_add_f32_e32 v72, v72, v122
	v_add_f32_e32 v72, v72, v123
	v_mul_f32_e32 v72, 0xbfb8aa3b, v72
	v_exp_f32_e32 v72, v72
	v_mul_f32_e32 v136, v107, v76
	v_fmac_f32_e32 v136, v109, v77
	v_lshlrev_b32_e32 v110, 16, v110
	v_add_f32_e32 v120, 1.0, v72
	v_fmac_f32_e32 v136, v75, v130

; DEV float silu_f(float x) { return x / (1.f + __expf(-x)); }
; DEV void gdn_sample_item(const Params& p, int item, unsigned char* lds) {
;     ...
;         for (int t = 0; t < 4; ++t) {
;             const float y = silu_f(wj[0] * x[t] + wj[1] * x[t + 1] + wj[2] * x[t + 2] + wj[3] * x[t + 3]);
;             if (m == 0) qv[t] = y; else if (m == 1) kv[t] = y; else vv[t] = y;
	v_fmac_f32_e32 v136, v74, v110

; DEV float silu_f(float x) { return x / (1.f + __expf(-x)); }
; DEV void gdn_sample_item(const Params& p, int item, unsigned char* lds) {
;     ...
;             const float y = silu_f(wj[0] * x[t] + wj[1] * x[t + 1] + wj[2] * x[t + 2] + wj[3] * x[t + 3]);
;     ...
;         gt[t] = __expf(-__expf(p.in[11][h]) * sp);
	v_mul_f32_e32 v109, 0xbfb8aa3b, v136
	v_exp_f32_e32 v109, v109
	v_mul_f32_e32 v73, v128, v129
	v_mul_f32_e32 v73, 0x3fb8aa3b, v73

; DEV void gdn_sample_item(const Params& p, int item, unsigned char* lds) {
;     ...
;         gt[t] = __expf(-__expf(p.in[11][h]) * sp);
	v_exp_f32_e32 v72, v73


; DEV float silu_f(float x) { return x / (1.f + __expf(-x)); }
; DEV void gdn_sample_item(const Params& p, int item, unsigned char* lds) {
;     ...
;             const float y = silu_f(wj[0] * x[t] + wj[1] * x[t + 1] + wj[2] * x[t + 2] + wj[3] * x[t + 3]);
	v_add_f32_e32 v109, 1.0, v109


; DEV void gdn_sample_item(const Params& p, int item, unsigned char* lds) {
;     ...
;         bt[t] = 1.f / (1.f + __expf(-bb));
	v_rcp_f32_e32 v73, v120
	s_nop 0
	v_mul_f32_e32 v73, 1.0, v73


; DEV void gdn_sample_item(const Params& p, int item, unsigned char* lds) {
;     ...
;         const float* kk = ksh + t * 128 + half * 64; const float* qq = qsh + t * 128 + half * 64;
;         f32x2_t ks2 = {0.f, 0.f};
; #pragma unroll
;         for (int d4 = 0; d4 < 16; ++d4) { const f32x4 k4 = *(const f32x4*)(kk + d4 * 4); ks2 += (f32x2_t){k4[0], k4[1]} * S[d4 * 2]; ks2 += (f32x2_t){k4[2], k4[3]} * S[d4 * 2 + 1]; }
	ds_read_b128 v[120:123], v111 offset:512
	ds_read_b128 v[132:135], v111 offset:528
	ds_read_b128 v[142:145], v111 offset:544
	ds_read_b128 v[146:149], v111 offset:560


; DEV void gdn_sample_item(const Params& p, int item, unsigned char* lds) {
;     ...
; #pragma unroll
;         for (int d4 = 0; d4 < 16; ++d4) { const f32x4 k4 = *(const f32x4*)(kk + d4 * 4); ks2 += (f32x2_t){k4[0], k4[1]} * S[d4 * 2]; ks2 += (f32x2_t){k4[2], k4[3]} * S[d4 * 2 + 1]; }
	s_waitcnt lgkmcnt(3)
	v_pk_fma_f32 v[120:121], v[10:11], v[120:121], 0 op_sel_hi:[1,1,0]

; DEV void gdn_sample_item(const Params& p, int item, unsigned char* lds) {
;     ...
; #pragma unroll
;         for (int d4 = 0; d4 < 16; ++d4) { const f32x4 k4 = *(const f32x4*)(kk + d4 * 4); ks2 += (f32x2_t){k4[0], k4[1]} * S[d4 * 2]; ks2 += (f32x2_t){k4[2], k4[3]} * S[d4 * 2 + 1]; }
	v_pk_fma_f32 v[120:121], v[12:13], v[122:123], v[120:121]

; DEV void gdn_sample_item(const Params& p, int item, unsigned char* lds) {
;     ...
; #pragma unroll
;         for (int d4 = 0; d4 < 16; ++d4) { const f32x4 k4 = *(const f32x4*)(kk + d4 * 4); ks2 += (f32x2_t){k4[0], k4[1]} * S[d4 * 2]; ks2 += (f32x2_t){k4[2], k4[3]} * S[d4 * 2 + 1]; }
	s_waitcnt lgkmcnt(2)
	v_pk_fma_f32 v[120:121], v[14:15], v[132:133], v[120:121]
	s_nop 0
	v_pk_fma_f32 v[120:121], v[16:17], v[134:135], v[120:121]
	ds_read_b128 v[132:135], v111 offset:592
	s_waitcnt lgkmcnt(2)
	v_pk_fma_f32 v[128:129], v[18:19], v[142:143], v[120:121]
	ds_read_b128 v[120:123], v111 offset:576
	v_pk_fma_f32 v[128:129], v[20:21], v[144:145], v[128:129]
	ds_read_b128 v[142:145], v111 offset:608
	s_waitcnt lgkmcnt(3)
	v_pk_fma_f32 v[128:129], v[22:23], v[146:147], v[128:129]
	s_nop 0
	v_pk_fma_f32 v[128:129], v[24:25], v[148:149], v[128:129]
	s_waitcnt lgkmcnt(1)
	v_pk_fma_f32 v[120:121], v[26:27], v[120:121], v[128:129]
	s_nop 0
	v_pk_fma_f32 v[120:121], v[28:29], v[122:123], v[120:121]
	s_nop 0
	v_pk_fma_f32 v[128:129], v[30:31], v[132:133], v[120:121]
	ds_read_b128 v[120:123], v111 offset:624
	v_pk_fma_f32 v[128:129], v[32:33], v[134:135], v[128:129]
	ds_read_b128 v[132:135], v111 offset:640
	s_waitcnt lgkmcnt(2)
	v_pk_fma_f32 v[128:129], v[34:35], v[142:143], v[128:129]
	s_nop 0
	v_pk_fma_f32 v[128:129], v[36:37], v[144:145], v[128:129]
	ds_read_b128 v[142:145], v111 offset:656
	s_waitcnt lgkmcnt(2)
	v_pk_fma_f32 v[120:121], v[38:39], v[120:121], v[128:129]
	s_nop 0
	v_pk_fma_f32 v[120:121], v[40:41], v[122:123], v[120:121]
	s_waitcnt lgkmcnt(1)
	v_pk_fma_f32 v[128:129], v[42:43], v[132:133], v[120:121]
	ds_read_b128 v[120:123], v111 offset:672
	v_pk_fma_f32 v[128:129], v[44:45], v[134:135], v[128:129]
	ds_read_b128 v[132:135], v111 offset:688
	s_waitcnt lgkmcnt(2)
	v_pk_fma_f32 v[128:129], v[46:47], v[142:143], v[128:129]
	s_nop 0
	v_pk_fma_f32 v[128:129], v[48:49], v[144:145], v[128:129]
	ds_read_b128 v[142:145], v111 offset:704
	s_waitcnt lgkmcnt(2)
	v_pk_fma_f32 v[120:121], v[50:51], v[120:121], v[128:129]
	s_nop 0
	v_pk_fma_f32 v[120:121], v[52:53], v[122:123], v[120:121]
	s_waitcnt lgkmcnt(1)
	v_pk_fma_f32 v[120:121], v[54:55], v[132:133], v[120:121]
	s_nop 0
	v_pk_fma_f32 v[128:129], v[56:57], v[134:135], v[120:121]
	ds_read_b128 v[120:123], v111 offset:720
	ds_read_b128 v[132:135], v111 offset:736
	s_waitcnt lgkmcnt(2)
	v_pk_fma_f32 v[128:129], v[58:59], v[142:143], v[128:129]
	s_nop 0
	v_pk_fma_f32 v[128:129], v[60:61], v[144:145], v[128:129]
	ds_read_b128 v[142:145], v111 offset:752
	s_waitcnt lgkmcnt(2)
	v_pk_fma_f32 v[120:121], v[62:63], v[120:121], v[128:129]
	s_nop 0
	v_pk_fma_f32 v[120:121], v[64:65], v[122:123], v[120:121]

; DEV void gdn_sample_item(const Params& p, int item, unsigned char* lds) {
;     ...
; #pragma unroll
;         for (int d4 = 0; d4 < 16; ++d4) { const f32x4 k4 = *(const f32x4*)(kk + d4 * 4); ks2 += (f32x2_t){k4[0], k4[1]} * S[d4 * 2]; ks2 += (f32x2_t){k4[2], k4[3]} * S[d4 * 2 + 1]; }
	s_waitcnt lgkmcnt(1)
	v_pk_fma_f32 v[120:121], v[66:67], v[132:133], v[120:121]

; DEV void gdn_sample_item(const Params& p, int item, unsigned char* lds) {
;     ...
;         part[(t * 2 + half) * 128 + c] = ks2[0] + ks2[1];
;         __syncthreads();
;         const float kS = part[(t * 2) * 128 + c] + part[(t * 2 + 1) * 128 + c];
;         const float eg = gt[t], dl = bt[t] * (vv[t] - eg * kS);
;         const f32x2_t eg2 = {eg, eg}, dl2 = {dl, dl};
;         f32x2_t o2 = {0.f, 0.f};
; #pragma unroll
;         for (int d4 = 0; d4 < 16; ++d4) {
;             const f32x4 k4 = *(const f32x4*)(kk + d4 * 4), q4 = *(const f32x4*)(qq + d4 * 4);
;             const f32x2_t s0 = S[d4 * 2] * eg2 + (f32x2_t){k4[0], k4[1]} * dl2, s1 = S[d4 * 2 + 1] * eg2 + (f32x2_t){k4[2], k4[3]} * dl2;
;             S[d4 * 2] = s0; S[d4 * 2 + 1] = s1;
;             o2 += (f32x2_t){q4[0], q4[1]} * s0; o2 += (f32x2_t){q4[2], q4[3]} * s1;
	v_pk_fma_f32 v[120:121], v[68:69], v[134:135], v[120:121]
	v_rcp_f32_e32 v122, v109
	s_nop 0
	v_mul_f32_e32 v109, v136, v122
	s_waitcnt lgkmcnt(0)
	v_pk_fma_f32 v[120:121], v[70:71], v[142:143], v[120:121]
	s_nop 0
	v_pk_fma_f32 v[120:121], v[8:9], v[144:145], v[120:121]
	s_nop 0
	v_add_f32_e32 v120, v120, v121
	ds_write_b32 v105, v120 offset:5376
	s_waitcnt lgkmcnt(0)
	s_barrier
	ds_read2st64_b32 v[120:121], v131 offset0:21 offset1:23
	s_waitcnt lgkmcnt(0)
	v_add_f32_e32 v120, v120, v121
	v_fma_f32 v109, -v72, v120, v109
	v_mul_f32_e32 v128, v73, v109
	ds_read_b128 v[120:123], v111 offset:512
	ds_read_b128 v[132:135], v111 offset:528
	ds_read_b128 v[142:145], v111 offset:544
	ds_read_b128 v[146:149], v111 offset:560
	ds_read_b128 v[150:153], v111 offset:2560
	s_waitcnt lgkmcnt(4)
	v_pk_mul_f32 v[120:121], v[120:121], v[128:129] op_sel_hi:[1,0]
	s_waitcnt lgkmcnt(3)
	v_pk_mul_f32 v[132:133], v[132:133], v[128:129] op_sel_hi:[1,0]
	v_pk_fma_f32 v[10:11], v[72:73], v[10:11], v[120:121] op_sel_hi:[0,1,1]
	v_pk_mul_f32 v[120:121], v[122:123], v[128:129] op_sel_hi:[1,0]
	s_waitcnt lgkmcnt(0)
	v_pk_fma_f32 v[136:137], v[150:151], v[10:11], 0 op_sel_hi:[1,1,0]
	v_pk_fma_f32 v[12:13], v[72:73], v[12:13], v[120:121] op_sel_hi:[0,1,1]
	ds_read_b128 v[120:123], v111 offset:2576
	v_pk_fma_f32 v[136:137], v[152:153], v[12:13], v[136:137]
	v_pk_fma_f32 v[14:15], v[72:73], v[14:15], v[132:133] op_sel_hi:[0,1,1]
	v_pk_mul_f32 v[132:133], v[134:135], v[128:129] op_sel_hi:[1,0]
	s_waitcnt lgkmcnt(0)
	v_pk_fma_f32 v[120:121], v[120:121], v[14:15], v[136:137]
	v_pk_fma_f32 v[16:17], v[72:73], v[16:17], v[132:133] op_sel_hi:[0,1,1]
	v_pk_fma_f32 v[136:137], v[122:123], v[16:17], v[120:121]
	ds_read_b128 v[120:123], v111 offset:2592
	v_pk_mul_f32 v[132:133], v[128:129], v[142:143] op_sel_hi:[0,1]
	v_pk_fma_f32 v[18:19], v[72:73], v[18:19], v[132:133] op_sel_hi:[0,1,1]
	v_pk_mul_f32 v[132:133], v[128:129], v[144:145] op_sel_hi:[0,1]
	v_pk_fma_f32 v[20:21], v[72:73], v[20:21], v[132:133] op_sel_hi:[0,1,1]
	ds_read_b128 v[132:135], v111 offset:2608
	s_waitcnt lgkmcnt(1)
	v_pk_fma_f32 v[120:121], v[120:121], v[18:19], v[136:137]
	s_nop 0
	v_pk_fma_f32 v[136:137], v[122:123], v[20:21], v[120:121]
	v_pk_mul_f32 v[120:121], v[128:129], v[146:147] op_sel_hi:[0,1]
	v_pk_fma_f32 v[22:23], v[72:73], v[22:23], v[120:121] op_sel_hi:[0,1,1]
	v_pk_mul_f32 v[120:121], v[128:129], v[148:149] op_sel_hi:[0,1]
	v_pk_fma_f32 v[24:25], v[72:73], v[24:25], v[120:121] op_sel_hi:[0,1,1]
	ds_read_b128 v[120:123], v111 offset:576
	s_waitcnt lgkmcnt(1)
	v_pk_fma_f32 v[132:133], v[132:133], v[22:23], v[136:137]
	s_waitcnt lgkmcnt(0)
	v_pk_mul_f32 v[120:121], v[128:129], v[120:121] op_sel_hi:[0,1]
	v_pk_fma_f32 v[136:137], v[134:135], v[24:25], v[132:133]
	ds_read_b128 v[132:135], v111 offset:2624
	ds_read_b128 v[142:145], v111 offset:592
	v_pk_fma_f32 v[26:27], v[72:73], v[26:27], v[120:121] op_sel_hi:[0,1,1]
	v_pk_mul_f32 v[120:121], v[128:129], v[122:123] op_sel_hi:[0,1]
	v_pk_fma_f32 v[28:29], v[72:73], v[28:29], v[120:121] op_sel_hi:[0,1,1]
	ds_read_b128 v[120:123], v111 offset:2640
	s_waitcnt lgkmcnt(2)
	v_pk_fma_f32 v[132:133], v[132:133], v[26:27], v[136:137]
	s_nop 0
	v_pk_fma_f32 v[136:137], v[134:135], v[28:29], v[132:133]
	s_waitcnt lgkmcnt(1)
	v_pk_mul_f32 v[132:133], v[128:129], v[142:143] op_sel_hi:[0,1]
	v_pk_fma_f32 v[30:31], v[72:73], v[30:31], v[132:133] op_sel_hi:[0,1,1]
	v_pk_mul_f32 v[132:133], v[128:129], v[144:145] op_sel_hi:[0,1]
	v_pk_fma_f32 v[32:33], v[72:73], v[32:33], v[132:133] op_sel_hi:[0,1,1]
	ds_read_b128 v[132:135], v111 offset:608
	s_waitcnt lgkmcnt(1)
	v_pk_fma_f32 v[120:121], v[120:121], v[30:31], v[136:137]
	s_waitcnt lgkmcnt(0)
	v_pk_mul_f32 v[132:133], v[128:129], v[132:133] op_sel_hi:[0,1]
	v_pk_fma_f32 v[136:137], v[122:123], v[32:33], v[120:121]
	ds_read_b128 v[120:123], v111 offset:2656
	ds_read_b128 v[142:145], v111 offset:624
	v_pk_fma_f32 v[34:35], v[72:73], v[34:35], v[132:133] op_sel_hi:[0,1,1]
	v_pk_mul_f32 v[132:133], v[128:129], v[134:135] op_sel_hi:[0,1]
	v_pk_fma_f32 v[36:37], v[72:73], v[36:37], v[132:133] op_sel_hi:[0,1,1]
	ds_read_b128 v[132:135], v111 offset:2672
	s_waitcnt lgkmcnt(2)
	v_pk_fma_f32 v[120:121], v[120:121], v[34:35], v[136:137]
	s_nop 0
	v_pk_fma_f32 v[136:137], v[122:123], v[36:37], v[120:121]
	s_waitcnt lgkmcnt(1)
	v_pk_mul_f32 v[120:121], v[128:129], v[142:143] op_sel_hi:[0,1]
	v_pk_fma_f32 v[38:39], v[72:73], v[38:39], v[120:121] op_sel_hi:[0,1,1]
	v_pk_mul_f32 v[120:121], v[128:129], v[144:145] op_sel_hi:[0,1]
	v_pk_fma_f32 v[40:41], v[72:73], v[40:41], v[120:121] op_sel_hi:[0,1,1]
	ds_read_b128 v[120:123], v111 offset:640
	s_waitcnt lgkmcnt(1)
	v_pk_fma_f32 v[132:133], v[132:133], v[38:39], v[136:137]
	s_waitcnt lgkmcnt(0)
; DEV void gdn_sample_item(const Params& p, int item, unsigned char* lds) {
;     ...
;         float a = 0.f, bb = 0.f;
; #pragma unroll
;         for (int kq = 0; kq < 4; ++kq) { a += ab[(size_t)kq * TT * 16 + (size_t)(r0 + t) * 16 + h]; bb += ab[(size_t)kq * TT * 16 + (size_t)(r0 + t) * 16 + 8 + h]; }
;         const float xx = a + p.in[12][h];
;         const float sp = xx > 20.f ? xx : log1pf(__expf(xx));
;         gt[t] = __expf(-__expf(p.in[11][h]) * sp);
;         bt[t] = 1.f / (1.f + __expf(-bb));
;     ...
;         for (int d4 = 0; d4 < 16; ++d4) {
;             const f32x4 k4 = *(const f32x4*)(kk + d4 * 4), q4 = *(const f32x4*)(qq + d4 * 4);
;             const f32x2_t s0 = S[d4 * 2] * eg2 + (f32x2_t){k4[0], k4[1]} * dl2, s1 = S[d4 * 2 + 1] * eg2 + (f32x2_t){k4[2], k4[3]} * dl2;
;             S[d4 * 2] = s0; S[d4 * 2 + 1] = s1;
;             o2 += (f32x2_t){q4[0], q4[1]} * s0; o2 += (f32x2_t){q4[2], q4[3]} * s1;
;         }
;         const float o = o2[0] + o2[1];
;         ot[t] = o;
;         if (half == 1) opart[t * 128 + c] = o;
;     }
	v_pk_mul_f32 v[120:121], v[128:129], v[120:121] op_sel_hi:[0,1]
	v_pk_fma_f32 v[136:137], v[134:135], v[40:41], v[132:133]
	ds_read_b128 v[132:135], v111 offset:2688
	ds_read_b128 v[142:145], v111 offset:656
	v_pk_fma_f32 v[42:43], v[72:73], v[42:43], v[120:121] op_sel_hi:[0,1,1]
	v_pk_mul_f32 v[120:121], v[128:129], v[122:123] op_sel_hi:[0,1]
	v_pk_fma_f32 v[44:45], v[72:73], v[44:45], v[120:121] op_sel_hi:[0,1,1]
	ds_read_b128 v[120:123], v111 offset:2704
	s_waitcnt lgkmcnt(2)
	v_pk_fma_f32 v[132:133], v[132:133], v[42:43], v[136:137]
	s_nop 0
	v_pk_fma_f32 v[136:137], v[134:135], v[44:45], v[132:133]
	s_waitcnt lgkmcnt(1)
	v_pk_mul_f32 v[132:133], v[128:129], v[142:143] op_sel_hi:[0,1]
	v_pk_fma_f32 v[46:47], v[72:73], v[46:47], v[132:133] op_sel_hi:[0,1,1]
	v_pk_mul_f32 v[132:133], v[128:129], v[144:145] op_sel_hi:[0,1]
	v_pk_fma_f32 v[48:49], v[72:73], v[48:49], v[132:133] op_sel_hi:[0,1,1]
	ds_read_b128 v[132:135], v111 offset:672
	s_waitcnt lgkmcnt(1)
	v_pk_fma_f32 v[120:121], v[120:121], v[46:47], v[136:137]
	s_waitcnt lgkmcnt(0)
	v_pk_mul_f32 v[132:133], v[128:129], v[132:133] op_sel_hi:[0,1]
	v_pk_fma_f32 v[136:137], v[122:123], v[48:49], v[120:121]
	ds_read_b128 v[120:123], v111 offset:2720
	ds_read_b128 v[142:145], v111 offset:688
	v_pk_fma_f32 v[50:51], v[72:73], v[50:51], v[132:133] op_sel_hi:[0,1,1]
	v_pk_mul_f32 v[132:133], v[128:129], v[134:135] op_sel_hi:[0,1]
	v_pk_fma_f32 v[52:53], v[72:73], v[52:53], v[132:133] op_sel_hi:[0,1,1]
	ds_read_b128 v[132:135], v111 offset:2736
	s_waitcnt lgkmcnt(2)
	v_pk_fma_f32 v[120:121], v[120:121], v[50:51], v[136:137]
	s_nop 0
	v_pk_fma_f32 v[136:137], v[122:123], v[52:53], v[120:121]
	s_waitcnt lgkmcnt(1)
	v_pk_mul_f32 v[120:121], v[128:129], v[142:143] op_sel_hi:[0,1]
	v_pk_fma_f32 v[54:55], v[72:73], v[54:55], v[120:121] op_sel_hi:[0,1,1]
	v_pk_mul_f32 v[120:121], v[128:129], v[144:145] op_sel_hi:[0,1]
	v_pk_fma_f32 v[56:57], v[72:73], v[56:57], v[120:121] op_sel_hi:[0,1,1]
	ds_read_b128 v[120:123], v111 offset:704
	s_waitcnt lgkmcnt(1)
	v_pk_fma_f32 v[132:133], v[132:133], v[54:55], v[136:137]
	s_waitcnt lgkmcnt(0)
	v_pk_mul_f32 v[120:121], v[128:129], v[120:121] op_sel_hi:[0,1]
	v_pk_fma_f32 v[136:137], v[134:135], v[56:57], v[132:133]
	ds_read_b128 v[132:135], v111 offset:2752
	ds_read_b128 v[142:145], v111 offset:720
	v_pk_fma_f32 v[58:59], v[72:73], v[58:59], v[120:121] op_sel_hi:[0,1,1]
	v_pk_mul_f32 v[120:121], v[128:129], v[122:123] op_sel_hi:[0,1]
	v_pk_fma_f32 v[60:61], v[72:73], v[60:61], v[120:121] op_sel_hi:[0,1,1]
	s_waitcnt lgkmcnt(1)
	v_pk_fma_f32 v[132:133], v[132:133], v[58:59], v[136:137]
	ds_read_b128 v[120:123], v111 offset:2768
	v_pk_fma_f32 v[136:137], v[134:135], v[60:61], v[132:133]
	s_waitcnt lgkmcnt(1)
	v_pk_mul_f32 v[132:133], v[128:129], v[142:143] op_sel_hi:[0,1]
	v_pk_fma_f32 v[62:63], v[72:73], v[62:63], v[132:133] op_sel_hi:[0,1,1]
	v_pk_mul_f32 v[132:133], v[128:129], v[144:145] op_sel_hi:[0,1]
	v_pk_fma_f32 v[64:65], v[72:73], v[64:65], v[132:133] op_sel_hi:[0,1,1]
	ds_read_b128 v[132:135], v111 offset:736
	s_waitcnt lgkmcnt(1)
	v_pk_fma_f32 v[120:121], v[120:121], v[62:63], v[136:137]
	s_waitcnt lgkmcnt(0)
	v_pk_mul_f32 v[132:133], v[128:129], v[132:133] op_sel_hi:[0,1]
	v_pk_fma_f32 v[136:137], v[122:123], v[64:65], v[120:121]
	ds_read_b128 v[120:123], v111 offset:2784
	ds_read_b128 v[142:145], v111 offset:752
	v_pk_fma_f32 v[66:67], v[72:73], v[66:67], v[132:133] op_sel_hi:[0,1,1]
	v_pk_mul_f32 v[132:133], v[128:129], v[134:135] op_sel_hi:[0,1]
	v_pk_fma_f32 v[68:69], v[72:73], v[68:69], v[132:133] op_sel_hi:[0,1,1]
	ds_read_b128 v[132:135], v111 offset:2800
	s_waitcnt lgkmcnt(2)
	v_pk_fma_f32 v[120:121], v[120:121], v[66:67], v[136:137]
	s_nop 0
	v_pk_fma_f32 v[120:121], v[122:123], v[68:69], v[120:121]
	s_waitcnt lgkmcnt(1)
	v_pk_mul_f32 v[122:123], v[128:129], v[142:143] op_sel_hi:[0,1]
	v_pk_fma_f32 v[70:71], v[72:73], v[70:71], v[122:123] op_sel_hi:[0,1,1]
	v_pk_mul_f32 v[122:123], v[128:129], v[144:145] op_sel_hi:[0,1]
	v_pk_fma_f32 v[8:9], v[72:73], v[8:9], v[122:123] op_sel_hi:[0,1,1]
	s_waitcnt lgkmcnt(0)
	v_pk_fma_f32 v[72:73], v[132:133], v[70:71], v[120:121]
	s_nop 0
	v_pk_fma_f32 v[72:73], v[134:135], v[8:9], v[72:73]
	s_nop 0
	v_add_f32_e32 v73, v72, v73
	s_and_saveexec_b64 s[52:53], s[8:9]
	ds_write_b32 v105, v73 offset:8448
	s_or_b64 exec, exec, s[52:53]
	v_add_f32_e32 v72, 0, v116
	v_add_f32_e32 v72, v72, v117
	v_add_f32_e32 v72, v72, v118
	v_add_f32_e32 v72, v72, v119
	v_mul_f32_e32 v72, 0xbfb8aa3b, v72
	v_exp_f32_e32 v72, v72
	v_mul_f32_e32 v136, v76, v130
	v_fmac_f32_e32 v136, v107, v77
	v_lshlrev_b32_e32 v108, 16, v108
	v_add_f32_e32 v116, 1.0, v72
	v_fmac_f32_e32 v136, v75, v110

; DEV float silu_f(float x) { return x / (1.f + __expf(-x)); }
; DEV void gdn_sample_item(const Params& p, int item, unsigned char* lds) {
;     ...
;         for (int t = 0; t < 4; ++t) {
;             const float y = silu_f(wj[0] * x[t] + wj[1] * x[t + 1] + wj[2] * x[t + 2] + wj[3] * x[t + 3]);
;             if (m == 0) qv[t] = y; else if (m == 1) kv[t] = y; else vv[t] = y;
	v_fmac_f32_e32 v136, v74, v108

; DEV float silu_f(float x) { return x / (1.f + __expf(-x)); }
; DEV void gdn_sample_item(const Params& p, int item, unsigned char* lds) {
;     ...
;             const float y = silu_f(wj[0] * x[t] + wj[1] * x[t + 1] + wj[2] * x[t + 2] + wj[3] * x[t + 3]);
;     ...
;         gt[t] = __expf(-__expf(p.in[11][h]) * sp);
	v_mul_f32_e32 v107, 0xbfb8aa3b, v136
	v_exp_f32_e32 v107, v107
	v_mul_f32_e32 v109, v126, v127
	v_mul_f32_e32 v109, 0x3fb8aa3b, v109

; DEV void gdn_sample_item(const Params& p, int item, unsigned char* lds) {
;     ...
;         gt[t] = __expf(-__expf(p.in[11][h]) * sp);
	v_exp_f32_e32 v72, v109


; DEV float silu_f(float x) { return x / (1.f + __expf(-x)); }
; DEV void gdn_sample_item(const Params& p, int item, unsigned char* lds) {
;     ...
;             const float y = silu_f(wj[0] * x[t] + wj[1] * x[t + 1] + wj[2] * x[t + 2] + wj[3] * x[t + 3]);
	v_add_f32_e32 v107, 1.0, v107


; DEV void gdn_sample_item(const Params& p, int item, unsigned char* lds) {
;     ...
;         bt[t] = 1.f / (1.f + __expf(-bb));
	v_rcp_f32_e32 v109, v116
	s_nop 0
	v_mul_f32_e32 v109, 1.0, v109


; DEV void gdn_sample_item(const Params& p, int item, unsigned char* lds) {
;     ...
;         const float* kk = ksh + t * 128 + half * 64; const float* qq = qsh + t * 128 + half * 64;
;         f32x2_t ks2 = {0.f, 0.f};
; #pragma unroll
;         for (int d4 = 0; d4 < 16; ++d4) { const f32x4 k4 = *(const f32x4*)(kk + d4 * 4); ks2 += (f32x2_t){k4[0], k4[1]} * S[d4 * 2]; ks2 += (f32x2_t){k4[2], k4[3]} * S[d4 * 2 + 1]; }
	ds_read_b128 v[116:119], v111 offset:1024


; DEV void gdn_sample_item(const Params& p, int item, unsigned char* lds) {
;     ...
; #pragma unroll
;         for (int d4 = 0; d4 < 16; ++d4) { const f32x4 k4 = *(const f32x4*)(kk + d4 * 4); ks2 += (f32x2_t){k4[0], k4[1]} * S[d4 * 2]; ks2 += (f32x2_t){k4[2], k4[3]} * S[d4 * 2 + 1]; }
	ds_read_b128 v[120:123], v111 offset:1040
	ds_read_b128 v[126:129], v111 offset:1056
	ds_read_b128 v[132:135], v111 offset:1072
	s_waitcnt lgkmcnt(3)
	v_pk_fma_f32 v[116:117], v[10:11], v[116:117], 0 op_sel_hi:[1,1,0]
	s_nop 0
	v_pk_fma_f32 v[116:117], v[12:13], v[118:119], v[116:117]
	s_waitcnt lgkmcnt(2)
	v_pk_fma_f32 v[116:117], v[14:15], v[120:121], v[116:117]
	s_nop 0
	v_pk_fma_f32 v[116:117], v[16:17], v[122:123], v[116:117]
	s_waitcnt lgkmcnt(1)
	v_pk_fma_f32 v[120:121], v[18:19], v[126:127], v[116:117]
	ds_read_b128 v[116:119], v111 offset:1088
	v_pk_fma_f32 v[120:121], v[20:21], v[128:129], v[120:121]
	s_waitcnt lgkmcnt(1)
	v_pk_fma_f32 v[126:127], v[22:23], v[132:133], v[120:121]
	ds_read_b128 v[120:123], v111 offset:1104
	v_pk_fma_f32 v[126:127], v[24:25], v[134:135], v[126:127]
	s_waitcnt lgkmcnt(1)
	v_pk_fma_f32 v[116:117], v[26:27], v[116:117], v[126:127]
	ds_read_b128 v[126:129], v111 offset:1120
	v_pk_fma_f32 v[116:117], v[28:29], v[118:119], v[116:117]
	s_waitcnt lgkmcnt(1)
	v_pk_fma_f32 v[120:121], v[30:31], v[120:121], v[116:117]
	ds_read_b128 v[116:119], v111 offset:1136
	v_pk_fma_f32 v[120:121], v[32:33], v[122:123], v[120:121]
	s_waitcnt lgkmcnt(1)
	v_pk_fma_f32 v[126:127], v[34:35], v[126:127], v[120:121]
	ds_read_b128 v[120:123], v111 offset:1152
	v_pk_fma_f32 v[126:127], v[36:37], v[128:129], v[126:127]
	s_waitcnt lgkmcnt(1)
	v_pk_fma_f32 v[116:117], v[38:39], v[116:117], v[126:127]
	ds_read_b128 v[126:129], v111 offset:1168
	v_pk_fma_f32 v[116:117], v[40:41], v[118:119], v[116:117]
	s_waitcnt lgkmcnt(1)
	v_pk_fma_f32 v[120:121], v[42:43], v[120:121], v[116:117]
	ds_read_b128 v[116:119], v111 offset:1184
	v_pk_fma_f32 v[120:121], v[44:45], v[122:123], v[120:121]
	s_waitcnt lgkmcnt(1)
	v_pk_fma_f32 v[126:127], v[46:47], v[126:127], v[120:121]
	ds_read_b128 v[120:123], v111 offset:1200
	v_pk_fma_f32 v[126:127], v[48:49], v[128:129], v[126:127]
	s_waitcnt lgkmcnt(1)
	v_pk_fma_f32 v[116:117], v[50:51], v[116:117], v[126:127]
	ds_read_b128 v[126:129], v111 offset:1216
	v_pk_fma_f32 v[116:117], v[52:53], v[118:119], v[116:117]
	s_waitcnt lgkmcnt(1)
	v_pk_fma_f32 v[116:117], v[54:55], v[120:121], v[116:117]
	s_nop 0
	v_pk_fma_f32 v[120:121], v[56:57], v[122:123], v[116:117]
	ds_read_b128 v[116:119], v111 offset:1232
	s_waitcnt lgkmcnt(1)
	v_pk_fma_f32 v[126:127], v[58:59], v[126:127], v[120:121]
	ds_read_b128 v[120:123], v111 offset:1248
	v_pk_fma_f32 v[132:133], v[60:61], v[128:129], v[126:127]
	ds_read_b128 v[126:129], v111 offset:1264
	s_waitcnt lgkmcnt(2)
	v_pk_fma_f32 v[116:117], v[62:63], v[116:117], v[132:133]
	s_nop 0
	v_pk_fma_f32 v[116:117], v[64:65], v[118:119], v[116:117]

; DEV void gdn_sample_item(const Params& p, int item, unsigned char* lds) {
;     ...
; #pragma unroll
;         for (int d4 = 0; d4 < 16; ++d4) { const f32x4 k4 = *(const f32x4*)(kk + d4 * 4); ks2 += (f32x2_t){k4[0], k4[1]} * S[d4 * 2]; ks2 += (f32x2_t){k4[2], k4[3]} * S[d4 * 2 + 1]; }
	s_waitcnt lgkmcnt(1)
	v_pk_fma_f32 v[116:117], v[66:67], v[120:121], v[116:117]

; DEV void gdn_sample_item(const Params& p, int item, unsigned char* lds) {
;     ...
;         part[(t * 2 + half) * 128 + c] = ks2[0] + ks2[1];
;         __syncthreads();
;         const float kS = part[(t * 2) * 128 + c] + part[(t * 2 + 1) * 128 + c];
;         const float eg = gt[t], dl = bt[t] * (vv[t] - eg * kS);
;         const f32x2_t eg2 = {eg, eg}, dl2 = {dl, dl};
;         f32x2_t o2 = {0.f, 0.f};
; #pragma unroll
;         for (int d4 = 0; d4 < 16; ++d4) {
;             const f32x4 k4 = *(const f32x4*)(kk + d4 * 4), q4 = *(const f32x4*)(qq + d4 * 4);
;             const f32x2_t s0 = S[d4 * 2] * eg2 + (f32x2_t){k4[0], k4[1]} * dl2, s1 = S[d4 * 2 + 1] * eg2 + (f32x2_t){k4[2], k4[3]} * dl2;
;             S[d4 * 2] = s0; S[d4 * 2 + 1] = s1;
;             o2 += (f32x2_t){q4[0], q4[1]} * s0; o2 += (f32x2_t){q4[2], q4[3]} * s1;
	v_pk_fma_f32 v[116:117], v[68:69], v[122:123], v[116:117]
	v_rcp_f32_e32 v118, v107
	s_nop 0
	v_mul_f32_e32 v107, v136, v118
	s_waitcnt lgkmcnt(0)
	v_pk_fma_f32 v[116:117], v[70:71], v[126:127], v[116:117]
	s_nop 0
	v_pk_fma_f32 v[116:117], v[8:9], v[128:129], v[116:117]
	s_nop 0
	v_add_f32_e32 v116, v116, v117
	ds_write_b32 v105, v116 offset:6400
	s_waitcnt lgkmcnt(0)
	s_barrier
	ds_read2st64_b32 v[116:117], v131 offset0:25 offset1:27
	s_waitcnt lgkmcnt(0)
	v_add_f32_e32 v116, v116, v117
	v_fma_f32 v107, -v72, v116, v107
	v_mul_f32_e32 v136, v109, v107
	ds_read_b128 v[116:119], v111 offset:1024
	ds_read_b128 v[120:123], v111 offset:1040
	ds_read_b128 v[126:129], v111 offset:1056
	ds_read_b128 v[132:135], v111 offset:1072
	ds_read_b128 v[142:145], v111 offset:3072
	s_waitcnt lgkmcnt(4)
	v_pk_mul_f32 v[116:117], v[116:117], v[136:137] op_sel_hi:[1,0]
	s_waitcnt lgkmcnt(3)
	v_pk_mul_f32 v[120:121], v[120:121], v[136:137] op_sel_hi:[1,0]
	v_pk_fma_f32 v[10:11], v[72:73], v[10:11], v[116:117] op_sel_hi:[0,1,1]
	v_pk_mul_f32 v[116:117], v[118:119], v[136:137] op_sel_hi:[1,0]
	s_waitcnt lgkmcnt(0)
	v_pk_fma_f32 v[142:143], v[142:143], v[10:11], 0 op_sel_hi:[1,1,0]
	v_pk_fma_f32 v[12:13], v[72:73], v[12:13], v[116:117] op_sel_hi:[0,1,1]
	ds_read_b128 v[116:119], v111 offset:3088
	v_pk_fma_f32 v[142:143], v[144:145], v[12:13], v[142:143]
	v_pk_fma_f32 v[14:15], v[72:73], v[14:15], v[120:121] op_sel_hi:[0,1,1]
	v_pk_mul_f32 v[120:121], v[122:123], v[136:137] op_sel_hi:[1,0]
	s_waitcnt lgkmcnt(0)
	v_pk_fma_f32 v[116:117], v[116:117], v[14:15], v[142:143]
	v_pk_fma_f32 v[16:17], v[72:73], v[16:17], v[120:121] op_sel_hi:[0,1,1]
	v_pk_fma_f32 v[142:143], v[118:119], v[16:17], v[116:117]
	ds_read_b128 v[116:119], v111 offset:3104
	v_pk_mul_f32 v[120:121], v[136:137], v[126:127] op_sel_hi:[0,1]
	v_pk_fma_f32 v[18:19], v[72:73], v[18:19], v[120:121] op_sel_hi:[0,1,1]
	v_pk_mul_f32 v[120:121], v[136:137], v[128:129] op_sel_hi:[0,1]
	v_pk_fma_f32 v[20:21], v[72:73], v[20:21], v[120:121] op_sel_hi:[0,1,1]
	ds_read_b128 v[120:123], v111 offset:3120
	s_waitcnt lgkmcnt(1)
	v_pk_fma_f32 v[116:117], v[116:117], v[18:19], v[142:143]
	s_nop 0
	v_pk_fma_f32 v[126:127], v[118:119], v[20:21], v[116:117]
	v_pk_mul_f32 v[116:117], v[136:137], v[132:133] op_sel_hi:[0,1]
	v_pk_fma_f32 v[22:23], v[72:73], v[22:23], v[116:117] op_sel_hi:[0,1,1]
	v_pk_mul_f32 v[116:117], v[136:137], v[134:135] op_sel_hi:[0,1]
	v_pk_fma_f32 v[24:25], v[72:73], v[24:25], v[116:117] op_sel_hi:[0,1,1]
	ds_read_b128 v[116:119], v111 offset:1088
	s_waitcnt lgkmcnt(1)
	v_pk_fma_f32 v[120:121], v[120:121], v[22:23], v[126:127]
	s_waitcnt lgkmcnt(0)
	v_pk_mul_f32 v[116:117], v[136:137], v[116:117] op_sel_hi:[0,1]
	v_pk_fma_f32 v[132:133], v[122:123], v[24:25], v[120:121]
	ds_read_b128 v[120:123], v111 offset:3136
	ds_read_b128 v[126:129], v111 offset:1104
	v_pk_fma_f32 v[26:27], v[72:73], v[26:27], v[116:117] op_sel_hi:[0,1,1]
	v_pk_mul_f32 v[116:117], v[136:137], v[118:119] op_sel_hi:[0,1]
	v_pk_fma_f32 v[28:29], v[72:73], v[28:29], v[116:117] op_sel_hi:[0,1,1]
	ds_read_b128 v[116:119], v111 offset:3152
	s_waitcnt lgkmcnt(2)
	v_pk_fma_f32 v[120:121], v[120:121], v[26:27], v[132:133]
	s_nop 0
	v_pk_fma_f32 v[132:133], v[122:123], v[28:29], v[120:121]
	s_waitcnt lgkmcnt(1)
	v_pk_mul_f32 v[120:121], v[136:137], v[126:127] op_sel_hi:[0,1]
	v_pk_fma_f32 v[30:31], v[72:73], v[30:31], v[120:121] op_sel_hi:[0,1,1]
	v_pk_mul_f32 v[120:121], v[136:137], v[128:129] op_sel_hi:[0,1]
	v_pk_fma_f32 v[32:33], v[72:73], v[32:33], v[120:121] op_sel_hi:[0,1,1]
	ds_read_b128 v[120:123], v111 offset:1120
	s_waitcnt lgkmcnt(1)
	v_pk_fma_f32 v[116:117], v[116:117], v[30:31], v[132:133]
	s_waitcnt lgkmcnt(0)
	v_pk_mul_f32 v[120:121], v[136:137], v[120:121] op_sel_hi:[0,1]
	v_pk_fma_f32 v[132:133], v[118:119], v[32:33], v[116:117]
	ds_read_b128 v[116:119], v111 offset:3168
	ds_read_b128 v[126:129], v111 offset:1136
	v_pk_fma_f32 v[34:35], v[72:73], v[34:35], v[120:121] op_sel_hi:[0,1,1]
	v_pk_mul_f32 v[120:121], v[136:137], v[122:123] op_sel_hi:[0,1]
	v_pk_fma_f32 v[36:37], v[72:73], v[36:37], v[120:121] op_sel_hi:[0,1,1]
	ds_read_b128 v[120:123], v111 offset:3184
	s_waitcnt lgkmcnt(2)
	v_pk_fma_f32 v[116:117], v[116:117], v[34:35], v[132:133]
	s_nop 0
	v_pk_fma_f32 v[132:133], v[118:119], v[36:37], v[116:117]
	s_waitcnt lgkmcnt(1)
	v_pk_mul_f32 v[116:117], v[136:137], v[126:127] op_sel_hi:[0,1]
	v_pk_fma_f32 v[38:39], v[72:73], v[38:39], v[116:117] op_sel_hi:[0,1,1]
	v_pk_mul_f32 v[116:117], v[136:137], v[128:129] op_sel_hi:[0,1]
	v_pk_fma_f32 v[40:41], v[72:73], v[40:41], v[116:117] op_sel_hi:[0,1,1]
	ds_read_b128 v[116:119], v111 offset:1152
	s_waitcnt lgkmcnt(1)
	v_pk_fma_f32 v[120:121], v[120:121], v[38:39], v[132:133]
	s_waitcnt lgkmcnt(0)
; DEV void gdn_sample_item(const Params& p, int item, unsigned char* lds) {
;     ...
;         float a = 0.f, bb = 0.f;
; #pragma unroll
;         for (int kq = 0; kq < 4; ++kq) { a += ab[(size_t)kq * TT * 16 + (size_t)(r0 + t) * 16 + h]; bb += ab[(size_t)kq * TT * 16 + (size_t)(r0 + t) * 16 + 8 + h]; }
;         const float xx = a + p.in[12][h];
;         const float sp = xx > 20.f ? xx : log1pf(__expf(xx));
;         gt[t] = __expf(-__expf(p.in[11][h]) * sp);
;         bt[t] = 1.f / (1.f + __expf(-bb));
;     ...
;         for (int d4 = 0; d4 < 16; ++d4) {
;             const f32x4 k4 = *(const f32x4*)(kk + d4 * 4), q4 = *(const f32x4*)(qq + d4 * 4);
;             const f32x2_t s0 = S[d4 * 2] * eg2 + (f32x2_t){k4[0], k4[1]} * dl2, s1 = S[d4 * 2 + 1] * eg2 + (f32x2_t){k4[2], k4[3]} * dl2;
;             S[d4 * 2] = s0; S[d4 * 2 + 1] = s1;
;             o2 += (f32x2_t){q4[0], q4[1]} * s0; o2 += (f32x2_t){q4[2], q4[3]} * s1;
;         }
;         const float o = o2[0] + o2[1];
;         ot[t] = o;
;         if (half == 1) opart[t * 128 + c] = o;
;     }
	v_pk_mul_f32 v[116:117], v[136:137], v[116:117] op_sel_hi:[0,1]
	v_pk_fma_f32 v[132:133], v[122:123], v[40:41], v[120:121]
	ds_read_b128 v[120:123], v111 offset:3200
	ds_read_b128 v[126:129], v111 offset:1168
	v_pk_fma_f32 v[42:43], v[72:73], v[42:43], v[116:117] op_sel_hi:[0,1,1]
	v_pk_mul_f32 v[116:117], v[136:137], v[118:119] op_sel_hi:[0,1]
	v_pk_fma_f32 v[44:45], v[72:73], v[44:45], v[116:117] op_sel_hi:[0,1,1]
	ds_read_b128 v[116:119], v111 offset:3216
	s_waitcnt lgkmcnt(2)
	v_pk_fma_f32 v[120:121], v[120:121], v[42:43], v[132:133]
	s_nop 0
	v_pk_fma_f32 v[132:133], v[122:123], v[44:45], v[120:121]
	s_waitcnt lgkmcnt(1)
	v_pk_mul_f32 v[120:121], v[136:137], v[126:127] op_sel_hi:[0,1]
	v_pk_fma_f32 v[46:47], v[72:73], v[46:47], v[120:121] op_sel_hi:[0,1,1]
	v_pk_mul_f32 v[120:121], v[136:137], v[128:129] op_sel_hi:[0,1]
	v_pk_fma_f32 v[48:49], v[72:73], v[48:49], v[120:121] op_sel_hi:[0,1,1]
	ds_read_b128 v[120:123], v111 offset:1184
	s_waitcnt lgkmcnt(1)
	v_pk_fma_f32 v[116:117], v[116:117], v[46:47], v[132:133]
	s_waitcnt lgkmcnt(0)
	v_pk_mul_f32 v[120:121], v[136:137], v[120:121] op_sel_hi:[0,1]
	v_pk_fma_f32 v[132:133], v[118:119], v[48:49], v[116:117]
	ds_read_b128 v[116:119], v111 offset:3232
	ds_read_b128 v[126:129], v111 offset:1200
	v_pk_fma_f32 v[50:51], v[72:73], v[50:51], v[120:121] op_sel_hi:[0,1,1]
	v_pk_mul_f32 v[120:121], v[136:137], v[122:123] op_sel_hi:[0,1]
	v_pk_fma_f32 v[52:53], v[72:73], v[52:53], v[120:121] op_sel_hi:[0,1,1]
	ds_read_b128 v[120:123], v111 offset:3248
	s_waitcnt lgkmcnt(2)
	v_pk_fma_f32 v[116:117], v[116:117], v[50:51], v[132:133]
	s_nop 0
	v_pk_fma_f32 v[132:133], v[118:119], v[52:53], v[116:117]
	s_waitcnt lgkmcnt(1)
	v_pk_mul_f32 v[116:117], v[136:137], v[126:127] op_sel_hi:[0,1]
	v_pk_fma_f32 v[54:55], v[72:73], v[54:55], v[116:117] op_sel_hi:[0,1,1]
	v_pk_mul_f32 v[116:117], v[136:137], v[128:129] op_sel_hi:[0,1]
	v_pk_fma_f32 v[56:57], v[72:73], v[56:57], v[116:117] op_sel_hi:[0,1,1]
	ds_read_b128 v[116:119], v111 offset:1216
	s_waitcnt lgkmcnt(1)
	v_pk_fma_f32 v[120:121], v[120:121], v[54:55], v[132:133]
	s_waitcnt lgkmcnt(0)
	v_pk_mul_f32 v[116:117], v[136:137], v[116:117] op_sel_hi:[0,1]
	v_pk_fma_f32 v[132:133], v[122:123], v[56:57], v[120:121]
	ds_read_b128 v[120:123], v111 offset:3264
	ds_read_b128 v[126:129], v111 offset:1232
	v_pk_fma_f32 v[58:59], v[72:73], v[58:59], v[116:117] op_sel_hi:[0,1,1]
	v_pk_mul_f32 v[116:117], v[136:137], v[118:119] op_sel_hi:[0,1]
	v_pk_fma_f32 v[60:61], v[72:73], v[60:61], v[116:117] op_sel_hi:[0,1,1]
	s_waitcnt lgkmcnt(1)
	v_pk_fma_f32 v[120:121], v[120:121], v[58:59], v[132:133]
	ds_read_b128 v[116:119], v111 offset:3280
	v_pk_fma_f32 v[132:133], v[122:123], v[60:61], v[120:121]
	s_waitcnt lgkmcnt(1)
	v_pk_mul_f32 v[120:121], v[136:137], v[126:127] op_sel_hi:[0,1]
	v_pk_fma_f32 v[62:63], v[72:73], v[62:63], v[120:121] op_sel_hi:[0,1,1]
	v_pk_mul_f32 v[120:121], v[136:137], v[128:129] op_sel_hi:[0,1]
	v_pk_fma_f32 v[64:65], v[72:73], v[64:65], v[120:121] op_sel_hi:[0,1,1]
	ds_read_b128 v[120:123], v111 offset:1248
	s_waitcnt lgkmcnt(1)
	v_pk_fma_f32 v[116:117], v[116:117], v[62:63], v[132:133]
	s_waitcnt lgkmcnt(0)
	v_pk_mul_f32 v[120:121], v[136:137], v[120:121] op_sel_hi:[0,1]
	v_pk_fma_f32 v[132:133], v[118:119], v[64:65], v[116:117]
	ds_read_b128 v[116:119], v111 offset:3296
	ds_read_b128 v[126:129], v111 offset:1264
	v_pk_fma_f32 v[66:67], v[72:73], v[66:67], v[120:121] op_sel_hi:[0,1,1]
	v_pk_mul_f32 v[120:121], v[136:137], v[122:123] op_sel_hi:[0,1]
	v_pk_fma_f32 v[68:69], v[72:73], v[68:69], v[120:121] op_sel_hi:[0,1,1]
	ds_read_b128 v[120:123], v111 offset:3312
	s_waitcnt lgkmcnt(2)
	v_pk_fma_f32 v[116:117], v[116:117], v[66:67], v[132:133]
	s_nop 0
	v_pk_fma_f32 v[116:117], v[118:119], v[68:69], v[116:117]
	s_waitcnt lgkmcnt(1)
	v_pk_mul_f32 v[118:119], v[136:137], v[126:127] op_sel_hi:[0,1]
	v_pk_fma_f32 v[70:71], v[72:73], v[70:71], v[118:119] op_sel_hi:[0,1,1]
	v_pk_mul_f32 v[118:119], v[136:137], v[128:129] op_sel_hi:[0,1]
	v_pk_fma_f32 v[8:9], v[72:73], v[8:9], v[118:119] op_sel_hi:[0,1,1]
	s_waitcnt lgkmcnt(0)
	v_pk_fma_f32 v[116:117], v[120:121], v[70:71], v[116:117]
	s_nop 0
	v_pk_fma_f32 v[116:117], v[122:123], v[8:9], v[116:117]
	s_nop 0
	v_add_f32_e32 v107, v116, v117
	s_and_saveexec_b64 s[52:53], s[8:9]
	ds_write_b32 v131, v107 offset:9472
	s_or_b64 exec, exec, s[52:53]
	v_add_f32_e32 v72, 0, v112
	v_add_f32_e32 v72, v72, v113
	v_add_f32_e32 v72, v72, v114
	v_add_f32_e32 v72, v72, v115
	v_mul_f32_e32 v72, 0xbfb8aa3b, v72
	v_exp_f32_e32 v72, v72
	v_mul_f32_e32 v110, v76, v110
	v_fmac_f32_e32 v110, v77, v130
	v_lshlrev_b32_e32 v106, 16, v106
	v_add_f32_e32 v112, 1.0, v72
	v_fmac_f32_e32 v110, v75, v108

; DEV float silu_f(float x) { return x / (1.f + __expf(-x)); }
; DEV void gdn_sample_item(const Params& p, int item, unsigned char* lds) {
;     ...
;         for (int t = 0; t < 4; ++t) {
;             const float y = silu_f(wj[0] * x[t] + wj[1] * x[t + 1] + wj[2] * x[t + 2] + wj[3] * x[t + 3]);
;             if (m == 0) qv[t] = y; else if (m == 1) kv[t] = y; else vv[t] = y;
	v_fmac_f32_e32 v110, v74, v106

; DEV float silu_f(float x) { return x / (1.f + __expf(-x)); }
; DEV void gdn_sample_item(const Params& p, int item, unsigned char* lds) {
;     ...
;             const float y = silu_f(wj[0] * x[t] + wj[1] * x[t + 1] + wj[2] * x[t + 2] + wj[3] * x[t + 3]);
;     ...
;         gt[t] = __expf(-__expf(p.in[11][h]) * sp);
	v_mul_f32_e32 v74, 0xbfb8aa3b, v110
	v_exp_f32_e32 v74, v74
	v_mul_f32_e32 v109, v124, v125
	v_mul_f32_e32 v109, 0x3fb8aa3b, v109

; DEV void gdn_sample_item(const Params& p, int item, unsigned char* lds) {
;     ...
;         gt[t] = __expf(-__expf(p.in[11][h]) * sp);
	v_exp_f32_e32 v72, v109


; DEV float silu_f(float x) { return x / (1.f + __expf(-x)); }
; DEV void gdn_sample_item(const Params& p, int item, unsigned char* lds) {
;     ...
;             const float y = silu_f(wj[0] * x[t] + wj[1] * x[t + 1] + wj[2] * x[t + 2] + wj[3] * x[t + 3]);
	v_add_f32_e32 v106, 1.0, v74


; DEV void gdn_sample_item(const Params& p, int item, unsigned char* lds) {
;     ...
;         bt[t] = 1.f / (1.f + __expf(-bb));
	v_rcp_f32_e32 v74, v112
	s_nop 0
	v_mul_f32_e32 v126, 1.0, v74


; DEV void gdn_sample_item(const Params& p, int item, unsigned char* lds) {
;     ...
;         const float* kk = ksh + t * 128 + half * 64; const float* qq = qsh + t * 128 + half * 64;
;         f32x2_t ks2 = {0.f, 0.f};
; #pragma unroll
;         for (int d4 = 0; d4 < 16; ++d4) { const f32x4 k4 = *(const f32x4*)(kk + d4 * 4); ks2 += (f32x2_t){k4[0], k4[1]} * S[d4 * 2]; ks2 += (f32x2_t){k4[2], k4[3]} * S[d4 * 2 + 1]; }
	ds_read_b128 v[74:77], v111 offset:1536
	ds_read_b128 v[112:115], v111 offset:1552
	ds_read_b128 v[116:119], v111 offset:1568
	ds_read_b128 v[120:123], v111 offset:1584


; DEV void gdn_sample_item(const Params& p, int item, unsigned char* lds) {
;     ...
; #pragma unroll
;         for (int d4 = 0; d4 < 16; ++d4) { const f32x4 k4 = *(const f32x4*)(kk + d4 * 4); ks2 += (f32x2_t){k4[0], k4[1]} * S[d4 * 2]; ks2 += (f32x2_t){k4[2], k4[3]} * S[d4 * 2 + 1]; }
	s_waitcnt lgkmcnt(3)
	v_pk_fma_f32 v[74:75], v[10:11], v[74:75], 0 op_sel_hi:[1,1,0]

; DEV void gdn_sample_item(const Params& p, int item, unsigned char* lds) {
;     ...
; #pragma unroll
;         for (int d4 = 0; d4 < 16; ++d4) { const f32x4 k4 = *(const f32x4*)(kk + d4 * 4); ks2 += (f32x2_t){k4[0], k4[1]} * S[d4 * 2]; ks2 += (f32x2_t){k4[2], k4[3]} * S[d4 * 2 + 1]; }
	v_pk_fma_f32 v[74:75], v[12:13], v[76:77], v[74:75]

; DEV void gdn_sample_item(const Params& p, int item, unsigned char* lds) {
;     ...
; #pragma unroll
;         for (int d4 = 0; d4 < 16; ++d4) { const f32x4 k4 = *(const f32x4*)(kk + d4 * 4); ks2 += (f32x2_t){k4[0], k4[1]} * S[d4 * 2]; ks2 += (f32x2_t){k4[2], k4[3]} * S[d4 * 2 + 1]; }
	s_waitcnt lgkmcnt(2)
	v_pk_fma_f32 v[74:75], v[14:15], v[112:113], v[74:75]
	s_nop 0
	v_pk_fma_f32 v[74:75], v[16:17], v[114:115], v[74:75]
	ds_read_b128 v[112:115], v111 offset:1616
	s_waitcnt lgkmcnt(2)
	v_pk_fma_f32 v[108:109], v[18:19], v[116:117], v[74:75]
	ds_read_b128 v[74:77], v111 offset:1600
	v_pk_fma_f32 v[108:109], v[20:21], v[118:119], v[108:109]
	ds_read_b128 v[116:119], v111 offset:1632
	s_waitcnt lgkmcnt(3)
	v_pk_fma_f32 v[108:109], v[22:23], v[120:121], v[108:109]
	s_nop 0
	v_pk_fma_f32 v[108:109], v[24:25], v[122:123], v[108:109]
	s_waitcnt lgkmcnt(1)
	v_pk_fma_f32 v[74:75], v[26:27], v[74:75], v[108:109]
	s_nop 0
	v_pk_fma_f32 v[74:75], v[28:29], v[76:77], v[74:75]
	s_nop 0
	v_pk_fma_f32 v[108:109], v[30:31], v[112:113], v[74:75]
	ds_read_b128 v[74:77], v111 offset:1648
	v_pk_fma_f32 v[108:109], v[32:33], v[114:115], v[108:109]
	ds_read_b128 v[112:115], v111 offset:1664
	s_waitcnt lgkmcnt(2)
	v_pk_fma_f32 v[108:109], v[34:35], v[116:117], v[108:109]
	s_nop 0
	v_pk_fma_f32 v[108:109], v[36:37], v[118:119], v[108:109]
	ds_read_b128 v[116:119], v111 offset:1680
	s_waitcnt lgkmcnt(2)
	v_pk_fma_f32 v[74:75], v[38:39], v[74:75], v[108:109]
	s_nop 0
	v_pk_fma_f32 v[74:75], v[40:41], v[76:77], v[74:75]
	s_waitcnt lgkmcnt(1)
	v_pk_fma_f32 v[108:109], v[42:43], v[112:113], v[74:75]
	ds_read_b128 v[74:77], v111 offset:1696
	v_pk_fma_f32 v[108:109], v[44:45], v[114:115], v[108:109]
	ds_read_b128 v[112:115], v111 offset:1712
	s_waitcnt lgkmcnt(2)
	v_pk_fma_f32 v[108:109], v[46:47], v[116:117], v[108:109]
	s_nop 0
	v_pk_fma_f32 v[108:109], v[48:49], v[118:119], v[108:109]
	ds_read_b128 v[116:119], v111 offset:1728
	s_waitcnt lgkmcnt(2)
	v_pk_fma_f32 v[74:75], v[50:51], v[74:75], v[108:109]
	s_nop 0
	v_pk_fma_f32 v[74:75], v[52:53], v[76:77], v[74:75]
	s_waitcnt lgkmcnt(1)
	v_pk_fma_f32 v[74:75], v[54:55], v[112:113], v[74:75]
	s_nop 0
	v_pk_fma_f32 v[108:109], v[56:57], v[114:115], v[74:75]
	ds_read_b128 v[74:77], v111 offset:1744
	ds_read_b128 v[112:115], v111 offset:1760
	s_waitcnt lgkmcnt(2)
	v_pk_fma_f32 v[108:109], v[58:59], v[116:117], v[108:109]
	s_nop 0
	v_pk_fma_f32 v[108:109], v[60:61], v[118:119], v[108:109]
	ds_read_b128 v[116:119], v111 offset:1776
	s_waitcnt lgkmcnt(2)
	v_pk_fma_f32 v[74:75], v[62:63], v[74:75], v[108:109]
	s_nop 0
	v_pk_fma_f32 v[74:75], v[64:65], v[76:77], v[74:75]

; DEV void gdn_sample_item(const Params& p, int item, unsigned char* lds) {
;     ...
; #pragma unroll
;         for (int d4 = 0; d4 < 16; ++d4) { const f32x4 k4 = *(const f32x4*)(kk + d4 * 4); ks2 += (f32x2_t){k4[0], k4[1]} * S[d4 * 2]; ks2 += (f32x2_t){k4[2], k4[3]} * S[d4 * 2 + 1]; }
	s_waitcnt lgkmcnt(1)
	v_pk_fma_f32 v[74:75], v[66:67], v[112:113], v[74:75]

; DEV void gdn_sample_item(const Params& p, int item, unsigned char* lds) {
;     ...
;         part[(t * 2 + half) * 128 + c] = ks2[0] + ks2[1];
;         __syncthreads();
;         const float kS = part[(t * 2) * 128 + c] + part[(t * 2 + 1) * 128 + c];
;         const float eg = gt[t], dl = bt[t] * (vv[t] - eg * kS);
;         const f32x2_t eg2 = {eg, eg}, dl2 = {dl, dl};
;         f32x2_t o2 = {0.f, 0.f};
; #pragma unroll
;         for (int d4 = 0; d4 < 16; ++d4) {
;             const f32x4 k4 = *(const f32x4*)(kk + d4 * 4), q4 = *(const f32x4*)(qq + d4 * 4);
;             const f32x2_t s0 = S[d4 * 2] * eg2 + (f32x2_t){k4[0], k4[1]} * dl2, s1 = S[d4 * 2 + 1] * eg2 + (f32x2_t){k4[2], k4[3]} * dl2;
;             S[d4 * 2] = s0; S[d4 * 2 + 1] = s1;
;             o2 += (f32x2_t){q4[0], q4[1]} * s0; o2 += (f32x2_t){q4[2], q4[3]} * s1;
;         }
	v_pk_fma_f32 v[74:75], v[68:69], v[114:115], v[74:75]
	v_rcp_f32_e32 v76, v106
	s_nop 0
	v_mul_f32_e32 v76, v110, v76
	s_waitcnt lgkmcnt(0)
	v_pk_fma_f32 v[74:75], v[70:71], v[116:117], v[74:75]
	s_nop 0
	v_pk_fma_f32 v[74:75], v[8:9], v[118:119], v[74:75]
	s_nop 0
	v_add_f32_e32 v74, v74, v75
	ds_write_b32 v105, v74 offset:7424
	s_waitcnt lgkmcnt(0)
	s_barrier
	ds_read2st64_b32 v[74:75], v131 offset0:29 offset1:31
	s_waitcnt lgkmcnt(0)
	v_add_f32_e32 v74, v74, v75
	v_fma_f32 v74, -v72, v74, v76
	v_mul_f32_e32 v106, v126, v74
	ds_read_b128 v[74:77], v111 offset:1536
	ds_read_b128 v[112:115], v111 offset:1552
	ds_read_b128 v[116:119], v111 offset:1568
	ds_read_b128 v[120:123], v111 offset:1584
	ds_read_b128 v[124:127], v111 offset:3584
	s_waitcnt lgkmcnt(4)
	v_pk_mul_f32 v[74:75], v[74:75], v[106:107] op_sel_hi:[1,0]
	ds_read_b128 v[128:131], v111 offset:3600
	v_pk_fma_f32 v[10:11], v[72:73], v[10:11], v[74:75] op_sel_hi:[0,1,1]
	v_pk_mul_f32 v[74:75], v[76:77], v[106:107] op_sel_hi:[1,0]
	s_nop 0
	v_pk_fma_f32 v[12:13], v[72:73], v[12:13], v[74:75] op_sel_hi:[0,1,1]
	s_waitcnt lgkmcnt(1)
	v_pk_fma_f32 v[74:75], v[124:125], v[10:11], 0 op_sel_hi:[1,1,0]
	s_nop 0
	v_pk_fma_f32 v[108:109], v[126:127], v[12:13], v[74:75]
	v_pk_mul_f32 v[74:75], v[112:113], v[106:107] op_sel_hi:[1,0]
	s_nop 0
	v_pk_fma_f32 v[74:75], v[72:73], v[14:15], v[74:75] op_sel_hi:[0,1,1]
	v_pk_mul_f32 v[14:15], v[114:115], v[106:107] op_sel_hi:[1,0]
	ds_read_b128 v[112:115], v111 offset:3616
	v_pk_fma_f32 v[76:77], v[72:73], v[16:17], v[14:15] op_sel_hi:[0,1,1]
	s_waitcnt lgkmcnt(1)
	v_pk_fma_f32 v[14:15], v[128:129], v[74:75], v[108:109]
	v_pk_mul_f32 v[16:17], v[106:107], v[118:119] op_sel_hi:[0,1]
	v_pk_fma_f32 v[108:109], v[130:131], v[76:77], v[14:15]
	v_pk_mul_f32 v[14:15], v[106:107], v[116:117] op_sel_hi:[0,1]
	v_pk_fma_f32 v[14:15], v[72:73], v[18:19], v[14:15] op_sel_hi:[0,1,1]
	ds_read_b128 v[116:119], v111 offset:3632
	v_pk_fma_f32 v[16:17], v[72:73], v[20:21], v[16:17] op_sel_hi:[0,1,1]
	s_waitcnt lgkmcnt(1)
	v_pk_fma_f32 v[18:19], v[112:113], v[14:15], v[108:109]
	v_pk_mul_f32 v[20:21], v[106:107], v[122:123] op_sel_hi:[0,1]
	v_pk_fma_f32 v[108:109], v[114:115], v[16:17], v[18:19]
	v_pk_mul_f32 v[18:19], v[106:107], v[120:121] op_sel_hi:[0,1]
	v_pk_fma_f32 v[18:19], v[72:73], v[22:23], v[18:19] op_sel_hi:[0,1,1]
	v_pk_fma_f32 v[20:21], v[72:73], v[24:25], v[20:21] op_sel_hi:[0,1,1]
	ds_read_b128 v[22:25], v111 offset:1600
	s_waitcnt lgkmcnt(1)
	v_pk_fma_f32 v[108:109], v[116:117], v[18:19], v[108:109]
	s_waitcnt lgkmcnt(0)
	v_pk_mul_f32 v[22:23], v[106:107], v[22:23] op_sel_hi:[0,1]
	v_pk_fma_f32 v[108:109], v[118:119], v[20:21], v[108:109]
	ds_read_b128 v[112:115], v111 offset:3648
	ds_read_b128 v[116:119], v111 offset:1616
	v_pk_fma_f32 v[22:23], v[72:73], v[26:27], v[22:23] op_sel_hi:[0,1,1]
	v_pk_mul_f32 v[24:25], v[106:107], v[24:25] op_sel_hi:[0,1]
	v_pk_fma_f32 v[24:25], v[72:73], v[28:29], v[24:25] op_sel_hi:[0,1,1]
	s_waitcnt lgkmcnt(1)
	v_pk_fma_f32 v[26:27], v[112:113], v[22:23], v[108:109]
	s_waitcnt lgkmcnt(0)
	v_pk_mul_f32 v[28:29], v[106:107], v[118:119] op_sel_hi:[0,1]
	v_pk_fma_f32 v[108:109], v[114:115], v[24:25], v[26:27]
	v_pk_mul_f32 v[26:27], v[106:107], v[116:117] op_sel_hi:[0,1]
	ds_read_b128 v[120:123], v111 offset:3664
	v_pk_fma_f32 v[26:27], v[72:73], v[30:31], v[26:27] op_sel_hi:[0,1,1]
	v_pk_fma_f32 v[28:29], v[72:73], v[32:33], v[28:29] op_sel_hi:[0,1,1]
	ds_read_b128 v[30:33], v111 offset:1632
	ds_read_b128 v[112:115], v111 offset:3680
	ds_read_b128 v[116:119], v111 offset:1648
	s_waitcnt lgkmcnt(3)
	v_pk_fma_f32 v[108:109], v[120:121], v[26:27], v[108:109]
	s_waitcnt lgkmcnt(2)
	v_pk_mul_f32 v[30:31], v[106:107], v[30:31] op_sel_hi:[0,1]
	v_pk_fma_f32 v[108:109], v[122:123], v[28:29], v[108:109]
	v_pk_fma_f32 v[30:31], v[72:73], v[34:35], v[30:31] op_sel_hi:[0,1,1]
	v_pk_mul_f32 v[32:33], v[106:107], v[32:33] op_sel_hi:[0,1]
	v_pk_fma_f32 v[32:33], v[72:73], v[36:37], v[32:33] op_sel_hi:[0,1,1]
	s_waitcnt lgkmcnt(1)
	v_pk_fma_f32 v[34:35], v[112:113], v[30:31], v[108:109]
	s_waitcnt lgkmcnt(0)
	v_pk_mul_f32 v[36:37], v[106:107], v[118:119] op_sel_hi:[0,1]
	v_pk_fma_f32 v[108:109], v[114:115], v[32:33], v[34:35]
	v_pk_mul_f32 v[34:35], v[106:107], v[116:117] op_sel_hi:[0,1]
	ds_read_b128 v[120:123], v111 offset:3696
	v_pk_fma_f32 v[34:35], v[72:73], v[38:39], v[34:35] op_sel_hi:[0,1,1]
	v_pk_fma_f32 v[36:37], v[72:73], v[40:41], v[36:37] op_sel_hi:[0,1,1]
	ds_read_b128 v[38:41], v111 offset:1664
	ds_read_b128 v[112:115], v111 offset:3712
	ds_read_b128 v[116:119], v111 offset:1680
	s_waitcnt lgkmcnt(3)
	v_pk_fma_f32 v[108:109], v[120:121], v[34:35], v[108:109]
	s_waitcnt lgkmcnt(2)
	v_pk_mul_f32 v[38:39], v[106:107], v[38:39] op_sel_hi:[0,1]
	v_pk_fma_f32 v[108:109], v[122:123], v[36:37], v[108:109]
	v_pk_fma_f32 v[38:39], v[72:73], v[42:43], v[38:39] op_sel_hi:[0,1,1]
	v_pk_mul_f32 v[40:41], v[106:107], v[40:41] op_sel_hi:[0,1]
	v_pk_fma_f32 v[40:41], v[72:73], v[44:45], v[40:41] op_sel_hi:[0,1,1]
	s_waitcnt lgkmcnt(1)
	v_pk_fma_f32 v[42:43], v[112:113], v[38:39], v[108:109]
	s_waitcnt lgkmcnt(0)
	v_pk_mul_f32 v[44:45], v[106:107], v[118:119] op_sel_hi:[0,1]
	v_pk_fma_f32 v[108:109], v[114:115], v[40:41], v[42:43]
	v_pk_mul_f32 v[42:43], v[106:107], v[116:117] op_sel_hi:[0,1]
	ds_read_b128 v[120:123], v111 offset:3728
	v_pk_fma_f32 v[42:43], v[72:73], v[46:47], v[42:43] op_sel_hi:[0,1,1]
	v_pk_fma_f32 v[44:45], v[72:73], v[48:49], v[44:45] op_sel_hi:[0,1,1]
	ds_read_b128 v[46:49], v111 offset:1696
	ds_read_b128 v[112:115], v111 offset:3744
	ds_read_b128 v[116:119], v111 offset:1712
	s_waitcnt lgkmcnt(3)
; DEV void gdn_sample_item(const Params& p, int item, unsigned char* lds) {
;     ...
;         for (int d4 = 0; d4 < 16; ++d4) {
;             const f32x4 k4 = *(const f32x4*)(kk + d4 * 4), q4 = *(const f32x4*)(qq + d4 * 4);
;             const f32x2_t s0 = S[d4 * 2] * eg2 + (f32x2_t){k4[0], k4[1]} * dl2, s1 = S[d4 * 2 + 1] * eg2 + (f32x2_t){k4[2], k4[3]} * dl2;
;             S[d4 * 2] = s0; S[d4 * 2 + 1] = s1;
;             o2 += (f32x2_t){q4[0], q4[1]} * s0; o2 += (f32x2_t){q4[2], q4[3]} * s1;
;         }
	v_pk_fma_f32 v[108:109], v[120:121], v[42:43], v[108:109]
	s_waitcnt lgkmcnt(2)
	v_pk_mul_f32 v[46:47], v[106:107], v[46:47] op_sel_hi:[0,1]
	v_pk_fma_f32 v[108:109], v[122:123], v[44:45], v[108:109]
	v_pk_fma_f32 v[46:47], v[72:73], v[50:51], v[46:47] op_sel_hi:[0,1,1]
	v_pk_mul_f32 v[48:49], v[106:107], v[48:49] op_sel_hi:[0,1]
	v_pk_fma_f32 v[48:49], v[72:73], v[52:53], v[48:49] op_sel_hi:[0,1,1]
	s_waitcnt lgkmcnt(1)
	v_pk_fma_f32 v[50:51], v[112:113], v[46:47], v[108:109]
	s_waitcnt lgkmcnt(0)
	v_pk_mul_f32 v[52:53], v[106:107], v[118:119] op_sel_hi:[0,1]
	v_pk_fma_f32 v[108:109], v[114:115], v[48:49], v[50:51]
	v_pk_mul_f32 v[50:51], v[106:107], v[116:117] op_sel_hi:[0,1]
	ds_read_b128 v[120:123], v111 offset:3760
	v_pk_fma_f32 v[50:51], v[72:73], v[54:55], v[50:51] op_sel_hi:[0,1,1]
	v_pk_fma_f32 v[52:53], v[72:73], v[56:57], v[52:53] op_sel_hi:[0,1,1]
	ds_read_b128 v[54:57], v111 offset:1728
	ds_read_b128 v[112:115], v111 offset:3776
	ds_read_b128 v[116:119], v111 offset:1744
	s_waitcnt lgkmcnt(3)
	v_pk_fma_f32 v[108:109], v[120:121], v[50:51], v[108:109]
	s_waitcnt lgkmcnt(2)
	v_pk_mul_f32 v[54:55], v[106:107], v[54:55] op_sel_hi:[0,1]
	v_pk_fma_f32 v[108:109], v[122:123], v[52:53], v[108:109]
	v_pk_fma_f32 v[54:55], v[72:73], v[58:59], v[54:55] op_sel_hi:[0,1,1]
	v_pk_mul_f32 v[56:57], v[106:107], v[56:57] op_sel_hi:[0,1]
	v_pk_fma_f32 v[56:57], v[72:73], v[60:61], v[56:57] op_sel_hi:[0,1,1]
	s_waitcnt lgkmcnt(1)
	v_pk_fma_f32 v[58:59], v[112:113], v[54:55], v[108:109]
	ds_read_b128 v[120:123], v111 offset:3792
	v_pk_fma_f32 v[108:109], v[114:115], v[56:57], v[58:59]
	s_waitcnt lgkmcnt(1)
	v_pk_mul_f32 v[58:59], v[106:107], v[116:117] op_sel_hi:[0,1]
	v_pk_mul_f32 v[60:61], v[106:107], v[118:119] op_sel_hi:[0,1]
	v_pk_fma_f32 v[58:59], v[72:73], v[62:63], v[58:59] op_sel_hi:[0,1,1]
	v_pk_fma_f32 v[60:61], v[72:73], v[64:65], v[60:61] op_sel_hi:[0,1,1]
	ds_read_b128 v[62:65], v111 offset:1760
	ds_read_b128 v[112:115], v111 offset:3808
	ds_read_b128 v[116:119], v111 offset:1776
	s_waitcnt lgkmcnt(3)
	v_pk_fma_f32 v[108:109], v[120:121], v[58:59], v[108:109]
	s_waitcnt lgkmcnt(2)
	v_pk_mul_f32 v[62:63], v[106:107], v[62:63] op_sel_hi:[0,1]
	v_pk_fma_f32 v[120:121], v[122:123], v[60:61], v[108:109]
	ds_read_b128 v[108:111], v111 offset:3824
	v_pk_fma_f32 v[62:63], v[72:73], v[66:67], v[62:63] op_sel_hi:[0,1,1]
	v_pk_mul_f32 v[64:65], v[106:107], v[64:65] op_sel_hi:[0,1]
	v_pk_fma_f32 v[64:65], v[72:73], v[68:69], v[64:65] op_sel_hi:[0,1,1]
	s_waitcnt lgkmcnt(2)
	v_pk_fma_f32 v[66:67], v[112:113], v[62:63], v[120:121]
	s_nop 0
	v_pk_fma_f32 v[68:69], v[114:115], v[64:65], v[66:67]
	s_waitcnt lgkmcnt(1)
	v_pk_mul_f32 v[66:67], v[106:107], v[116:117] op_sel_hi:[0,1]
	v_pk_fma_f32 v[66:67], v[72:73], v[70:71], v[66:67] op_sel_hi:[0,1,1]
	v_pk_mul_f32 v[70:71], v[106:107], v[118:119] op_sel_hi:[0,1]
	v_pk_fma_f32 v[8:9], v[72:73], v[8:9], v[70:71] op_sel_hi:[0,1,1]
	s_waitcnt lgkmcnt(0)
; DEV void gdn_sample_item(const Params& p, int item, unsigned char* lds) {
;     ...
;             o2 += (f32x2_t){q4[0], q4[1]} * s0; o2 += (f32x2_t){q4[2], q4[3]} * s1;
;         }
;         const float o = o2[0] + o2[1];
;         ot[t] = o;
;         if (half == 1) opart[t * 128 + c] = o;
;     }
;     float* dso = p.out + O_DS + ((size_t)(sb * 8 + h) * 128 + half * 64) * 128 + c;
; #pragma unroll
;     for (int d = 0; d < 64; ++d) __builtin_nontemporal_store(S[d >> 1][d & 1], dso + (size_t)d * 128);
;     __syncthreads();
;     if (half == 0) {
; #pragma unroll
;         for (int t = 0; t < 4; ++t) { ot[t] += opart[t * 128 + c]; const float a = wave_sum(ot[t] * ot[t]); if (lane == 0) red2[wid * 4 + t] = a; }
;     }
	v_pk_fma_f32 v[68:69], v[108:109], v[66:67], v[68:69]
	s_nop 0
	v_pk_fma_f32 v[68:69], v[110:111], v[8:9], v[68:69]
	s_nop 0
	v_add_f32_e32 v68, v68, v69
	s_and_saveexec_b64 s[52:53], s[8:9]
	v_lshl_or_b32 v69, v97, 2, v94
	v_add_u32_e32 v69, s70, v69
	ds_write_b32 v69, v68 offset:8448
	s_or_b64 exec, exec, s[52:53]
	v_lshl_add_u64 v[6:7], v[6:7], 2, s[12:13]
	v_lshl_add_u64 v[6:7], v[6:7], 0, v[2:3]
	global_store_dword v[6:7], v10, off nt
	global_store_dword v[6:7], v11, off offset:512 nt
	global_store_dword v[6:7], v12, off offset:1024 nt
	global_store_dword v[6:7], v13, off offset:1536 nt
	global_store_dword v[6:7], v74, off offset:2048 nt
	global_store_dword v[6:7], v75, off offset:2560 nt
	global_store_dword v[6:7], v76, off offset:3072 nt
	global_store_dword v[6:7], v77, off offset:3584 nt
	v_add_co_u32_e32 v10, vcc, s85, v6
	s_nop 1
	v_addc_co_u32_e32 v11, vcc, 0, v7, vcc
	v_add_co_u32_e32 v12, vcc, s65, v6
	s_nop 1
	v_addc_co_u32_e32 v13, vcc, 0, v7, vcc
	global_store_dword v[12:13], v14, off offset:-4096 nt
	global_store_dword v[10:11], v15, off offset:512 nt
	global_store_dword v[10:11], v16, off offset:1024 nt
	global_store_dword v[10:11], v17, off offset:1536 nt
	global_store_dword v[10:11], v18, off offset:2048 nt
	global_store_dword v[10:11], v19, off offset:2560 nt
	global_store_dword v[10:11], v20, off offset:3072 nt
	global_store_dword v[10:11], v21, off offset:3584 nt
	global_store_dword v[12:13], v22, off nt
	global_store_dword v[12:13], v23, off offset:512 nt
	global_store_dword v[12:13], v24, off offset:1024 nt
	global_store_dword v[12:13], v25, off offset:1536 nt
	global_store_dword v[12:13], v26, off offset:2048 nt
	global_store_dword v[12:13], v27, off offset:2560 nt
	global_store_dword v[12:13], v28, off offset:3072 nt
	global_store_dword v[12:13], v29, off offset:3584 nt
	v_add_co_u32_e32 v10, vcc, s66, v6
	s_nop 1
	v_addc_co_u32_e32 v11, vcc, 0, v7, vcc
	v_add_co_u32_e32 v12, vcc, s68, v6
	s_nop 1
	v_addc_co_u32_e32 v13, vcc, 0, v7, vcc
	global_store_dword v[12:13], v30, off offset:-4096 nt
	global_store_dword v[10:11], v31, off offset:512 nt
	global_store_dword v[10:11], v32, off offset:1024 nt
	global_store_dword v[10:11], v33, off offset:1536 nt
	global_store_dword v[10:11], v34, off offset:2048 nt
	global_store_dword v[10:11], v35, off offset:2560 nt
	global_store_dword v[10:11], v36, off offset:3072 nt
	global_store_dword v[10:11], v37, off offset:3584 nt
	global_store_dword v[12:13], v38, off nt
	global_store_dword v[12:13], v39, off offset:512 nt
	global_store_dword v[12:13], v40, off offset:1024 nt
	global_store_dword v[12:13], v41, off offset:1536 nt
	global_store_dword v[12:13], v42, off offset:2048 nt
	global_store_dword v[12:13], v43, off offset:2560 nt
	global_store_dword v[12:13], v44, off offset:3072 nt
	global_store_dword v[12:13], v45, off offset:3584 nt
	v_add_co_u32_e32 v10, vcc, s74, v6
	s_nop 1
	v_addc_co_u32_e32 v11, vcc, 0, v7, vcc
	v_add_co_u32_e32 v12, vcc, s67, v6
	s_nop 1
	v_addc_co_u32_e32 v13, vcc, 0, v7, vcc
	v_add_co_u32_e32 v6, vcc, s69, v6
	global_store_dword v[12:13], v46, off offset:-4096 nt
	global_store_dword v[10:11], v47, off offset:512 nt
	global_store_dword v[10:11], v48, off offset:1024 nt
	global_store_dword v[10:11], v49, off offset:1536 nt
	global_store_dword v[10:11], v50, off offset:2048 nt
	global_store_dword v[10:11], v51, off offset:2560 nt
	global_store_dword v[10:11], v52, off offset:3072 nt
	global_store_dword v[10:11], v53, off offset:3584 nt
	global_store_dword v[12:13], v54, off nt
	global_store_dword v[12:13], v55, off offset:512 nt
	global_store_dword v[12:13], v56, off offset:1024 nt
	global_store_dword v[12:13], v57, off offset:1536 nt
	global_store_dword v[12:13], v58, off offset:2048 nt
	global_store_dword v[12:13], v59, off offset:2560 nt
	global_store_dword v[12:13], v60, off offset:3072 nt
	global_store_dword v[12:13], v61, off offset:3584 nt
	v_addc_co_u32_e32 v7, vcc, 0, v7, vcc
	global_store_dword v[6:7], v62, off nt
	global_store_dword v[6:7], v63, off offset:512 nt
	global_store_dword v[6:7], v64, off offset:1024 nt
	global_store_dword v[6:7], v65, off offset:1536 nt
	global_store_dword v[6:7], v66, off offset:2048 nt
	global_store_dword v[6:7], v67, off offset:2560 nt
	global_store_dword v[6:7], v8, off offset:3072 nt
	global_store_dword v[6:7], v9, off offset:3584 nt
	s_waitcnt lgkmcnt(0)
	s_barrier
	s_and_saveexec_b64 s[8:9], s[6:7]
	s_cbranch_execz .LBB0_866
	ds_read_b32 v6, v105 offset:8448
	s_waitcnt lgkmcnt(0)
	v_add_f32_e32 v5, v5, v6
	v_mul_f32_e32 v6, v5, v5
	ds_bpermute_b32 v6, v98, v6
	s_waitcnt lgkmcnt(0)
	v_fmac_f32_e32 v6, v5, v5
	ds_bpermute_b32 v7, v99, v6
	s_waitcnt lgkmcnt(0)
	v_add_f32_e32 v6, v6, v7
	ds_bpermute_b32 v7, v100, v6
	s_waitcnt lgkmcnt(0)
	v_add_f32_e32 v6, v6, v7
	ds_bpermute_b32 v7, v101, v6
	s_waitcnt lgkmcnt(0)
	v_add_f32_e32 v6, v6, v7
	ds_bpermute_b32 v7, v102, v6
	s_waitcnt lgkmcnt(0)
	v_add_f32_e32 v7, v6, v7
	ds_bpermute_b32 v8, v103, v7
	v_lshlrev_b32_e32 v6, 2, v104
	v_lshl_add_u32 v6, v6, 2, s70
	s_and_saveexec_b64 s[52:53], s[4:5]
	s_cbranch_execz .LBB0_859
	s_waitcnt lgkmcnt(0)
	v_add_f32_e32 v7, v7, v8
	ds_write_b32 v6, v7 offset:4224
